# AC
# speedup vs baseline: 1.0107x; 1.0107x over previous
; #define WAIT_L(n) asm volatile("s_waitcnt lgkmcnt(" #n ")" ::: "memory")
; #define BAR __builtin_amdgcn_s_barrier()
; template <int MODE, int N>
; __device__ __forceinline__ void gemm_phase(const bf16_t* __restrict__ A, const bf16_t* __restrict__ Bt,
;                            bf16_t* __restrict__ Cb, float* __restrict__ Cf, const float* __restrict__ resid,
;                            float alpha) {
;     ...
; #pragma unroll
;       for (int ai = 0; ai < 2; ++ai) {
;         {
;           int el0 = gtid;
;           asm volatile("" : "+v"(el0));
;           char* lb = cst + (((el0 >> 8) & 1) * 64 + (el0 & 15)) * CROW + (((el0 >> 6) & 3) * 32 + ((el0 >> 4) & 3) * 4) * 2;
;           for (int bj = 0; bj < 2; ++bj)
;             for (int m = 0; m < 4; ++m)
;               for (int n = 0; n < 2; ++n) {
;                 f32x4 v = acc[ai][bj][m][n];
;                 uint2 o;
;                 o.x = pack2(v[0], v[1]);
;                 o.y = pack2(v[2], v[3]);
;                 *(uint2*)(lb + m * 16 * CROW + bj * HALF * 2 + n * 32) = o;
;               }
;         }
;         WAIT_L(0);
;         BAR;
;         asm volatile("" ::: "memory");
;         {
;           int el = gtid;
;           asm volatile("" : "+v"(el));
;           const int rsub = (el >> 5) & 1, cch = el & 31, rl0 = (el >> 6) * 16 + rsub;
;           bf16_t* cptr = Cb + (size_t)(brow + ai * HALF + rl0) * N + bcol + cch * 8;
;           const char* lptr = cst + rl0 * CROW + cch * 16;
; #pragma unroll
;           for (int i = 0; i < 8; ++i) {
;             typedef unsigned u32x4 __attribute__((ext_vector_type(4)));
;             u32x4 v = *(const u32x4*)(lptr + i * 2 * CROW);
;             __builtin_nontemporal_store(v, (u32x4*)cptr);
;             cptr += 2 * N;
;           }
;         }
;         WAIT_L(0);
;         BAR;
;         asm volatile("" ::: "memory");
.LBB0_130:
	v_mov_b32_e32 v132, v150
	v_cvt_pk_bf16_f32 v92, v92, v93
	v_lshrrev_b32_e32 v142, 2, v132
	v_and_b32_e32 v143, 15, v132
	v_and_or_b32 v142, v142, 64, v143
	v_mov_b32_e32 v143, s66
	v_lshrrev_b32_e32 v144, 1, v132
	v_mad_u32_u24 v142, v142, s68, v143
	v_and_b32_e32 v144, 24, v144
	v_and_b32_e32 v132, 0xc0, v132
	v_add3_u32 v132, v142, v132, v144
	v_cvt_pk_bf16_f32 v93, v94, v95
	v_cvt_pk_bf16_f32 v84, v84, v85
	v_cvt_pk_bf16_f32 v85, v86, v87
	v_add_u32_e32 v94, 0x6000, v132
	ds_write2_b64 v94, v[92:93], v[84:85] offset0:96 offset1:100
	v_cvt_pk_bf16_f32 v84, v104, v105
	v_cvt_pk_bf16_f32 v85, v106, v107
	v_cvt_pk_bf16_f32 v86, v96, v97
	v_cvt_pk_bf16_f32 v87, v98, v99
	v_cvt_pk_bf16_f32 v124, v124, v125
	v_cvt_pk_bf16_f32 v125, v126, v127
	v_cvt_pk_bf16_f32 v120, v120, v121
	v_cvt_pk_bf16_f32 v121, v122, v123
	v_cvt_pk_bf16_f32 v116, v116, v117
	v_cvt_pk_bf16_f32 v117, v118, v119
	v_cvt_pk_bf16_f32 v112, v112, v113
	v_cvt_pk_bf16_f32 v113, v114, v115
	v_add_u32_e32 v114, 0x2000, v132
	v_cvt_pk_bf16_f32 v108, v108, v109
	v_cvt_pk_bf16_f32 v109, v110, v111
	v_cvt_pk_bf16_f32 v100, v100, v101
	v_cvt_pk_bf16_f32 v101, v102, v103
	v_add_u32_e32 v102, 0x4000, v132
	ds_write2_b64 v132, v[84:85], v[86:87] offset0:32 offset1:36
	v_cvt_pk_bf16_f32 v84, v88, v89
	v_cvt_pk_bf16_f32 v85, v90, v91
	v_cvt_pk_bf16_f32 v80, v80, v81
	v_cvt_pk_bf16_f32 v81, v82, v83
	v_cvt_pk_bf16_f32 v76, v76, v77
	v_cvt_pk_bf16_f32 v77, v78, v79
	v_cvt_pk_bf16_f32 v72, v72, v73
	v_cvt_pk_bf16_f32 v73, v74, v75
	v_cvt_pk_bf16_f32 v68, v68, v69
	v_cvt_pk_bf16_f32 v69, v70, v71
	v_cvt_pk_bf16_f32 v64, v64, v65
	v_cvt_pk_bf16_f32 v65, v66, v67
	ds_write2_b64 v132, v[124:125], v[120:121] offset1:4
	ds_write2_b64 v114, v[116:117], v[112:113] offset0:32 offset1:36
	ds_write2_b64 v102, v[108:109], v[100:101] offset0:64 offset1:68
	ds_write2_b64 v114, v[84:85], v[80:81] offset0:64 offset1:68
	ds_write2_b64 v102, v[76:77], v[72:73] offset0:96 offset1:100
	ds_write2_b64 v94, v[68:69], v[64:65] offset0:128 offset1:132
	v_mov_b32_e32 v64, v150
	s_waitcnt lgkmcnt(0)
	s_barrier
	s_lshl_b64 s[46:47], s[46:47], 1
	v_bfe_u32 v65, v64, 5, 1
	v_ashrrev_i32_e32 v66, 2, v64
	v_and_or_b32 v65, v66, -16, v65
	v_lshlrev_b32_e32 v64, 4, v64
	s_add_u32 s46, s25, s46
	v_and_b32_e32 v132, 0x1f0, v64
	v_mul_lo_u32 v64, v65, s68
	s_addc_u32 s47, s56, s47
	v_add3_u32 v78, s66, v64, v132
	v_add_u32_e32 v68, s44, v65
	v_mov_b64_e32 v[72:73], s[46:47]
	ds_read_b128 v[64:67], v78
	v_mad_i64_i32 v[68:69], s[44:45], v68, s69, v[72:73]
	v_lshl_add_u64 v[74:75], v[68:69], 0, v[132:133]
	ds_read_b128 v[68:71], v78 offset:1056
	s_waitcnt lgkmcnt(0)
	global_store_dwordx4 v[74:75], v[64:67], off nt
	v_cvt_pk_bf16_f32 v60, v60, v61
	v_cvt_pk_bf16_f32 v61, v62, v63
	v_add_co_u32_e32 v64, vcc, s71, v74
	v_cvt_pk_bf16_f32 v56, v56, v57
	s_nop 0
	v_addc_co_u32_e32 v65, vcc, 0, v75, vcc
	global_store_dwordx4 v[64:65], v[68:71], off offset:1024 nt
	ds_read_b128 v[64:67], v78 offset:2112
	ds_read_b128 v[68:71], v78 offset:3168
	v_add_co_u32_e32 v76, vcc, s67, v74
	v_cvt_pk_bf16_f32 v57, v58, v59
	s_nop 0
	v_addc_co_u32_e32 v77, vcc, 0, v75, vcc
	s_waitcnt lgkmcnt(0)
	global_store_dwordx4 v[76:77], v[64:67], off offset:2048 nt
	v_cvt_pk_bf16_f32 v52, v52, v53
	v_cvt_pk_bf16_f32 v53, v54, v55
	v_add_co_u32_e32 v64, vcc, s72, v74
	v_cvt_pk_bf16_f32 v48, v48, v49
	s_nop 0
	v_addc_co_u32_e32 v65, vcc, 0, v75, vcc
	global_store_dwordx4 v[64:65], v[68:71], off offset:3072 nt
	ds_read_b128 v[64:67], v78 offset:4224
	ds_read_b128 v[68:71], v78 offset:5280
	v_add_co_u32_e32 v76, vcc, s73, v74
	v_cvt_pk_bf16_f32 v49, v50, v51
	s_nop 0
	v_addc_co_u32_e32 v77, vcc, 0, v75, vcc
	s_waitcnt lgkmcnt(0)
	global_store_dwordx4 v[76:77], v[64:67], off nt
	v_cvt_pk_bf16_f32 v44, v44, v45
	v_cvt_pk_bf16_f32 v45, v46, v47
	v_add_co_u32_e32 v64, vcc, s74, v74
	v_cvt_pk_bf16_f32 v40, v40, v41
	s_nop 0
	v_addc_co_u32_e32 v65, vcc, 0, v75, vcc
	global_store_dwordx4 v[64:65], v[68:71], off offset:1024 nt
	ds_read_b128 v[64:67], v78 offset:6336
	ds_read_b128 v[68:71], v78 offset:7392
	v_add_co_u32_e32 v76, vcc, s75, v74
	v_cvt_pk_bf16_f32 v41, v42, v43
	s_nop 0
	v_addc_co_u32_e32 v77, vcc, 0, v75, vcc
	s_waitcnt lgkmcnt(0)
	global_store_dwordx4 v[76:77], v[64:67], off offset:2048 nt
	v_cvt_pk_bf16_f32 v36, v36, v37
	v_cvt_pk_bf16_f32 v37, v38, v39
	v_add_co_u32_e32 v64, vcc, s76, v74
	v_cvt_pk_bf16_f32 v32, v32, v33
	s_nop 0
	v_addc_co_u32_e32 v65, vcc, 0, v75, vcc
	global_store_dwordx4 v[64:65], v[68:71], off offset:3072 nt
	v_mov_b32_e32 v64, v150
	s_waitcnt lgkmcnt(0)
	s_barrier
; #define WAIT_L(n) asm volatile("s_waitcnt lgkmcnt(" #n ")" ::: "memory")
; #define BAR __builtin_amdgcn_s_barrier()
; template <int MODE, int N>
; __device__ __forceinline__ void gemm_phase(const bf16_t* __restrict__ A, const bf16_t* __restrict__ Bt,
;                            bf16_t* __restrict__ Cb, float* __restrict__ Cf, const float* __restrict__ resid,
;                            float alpha) {
;     ...
;         {
;           int el0 = gtid;
;           asm volatile("" : "+v"(el0));
;           char* lb = cst + (((el0 >> 8) & 1) * 64 + (el0 & 15)) * CROW + (((el0 >> 6) & 3) * 32 + ((el0 >> 4) & 3) * 4) * 2;
;           for (int bj = 0; bj < 2; ++bj)
;             for (int m = 0; m < 4; ++m)
;               for (int n = 0; n < 2; ++n) {
;                 f32x4 v = acc[ai][bj][m][n];
;                 uint2 o;
;                 o.x = pack2(v[0], v[1]);
;                 o.y = pack2(v[2], v[3]);
;                 *(uint2*)(lb + m * 16 * CROW + bj * HALF * 2 + n * 32) = o;
;               }
;         }
;         WAIT_L(0);
;         BAR;
;         asm volatile("" ::: "memory");
;         {
;           int el = gtid;
;           asm volatile("" : "+v"(el));
;           const int rsub = (el >> 5) & 1, cch = el & 31, rl0 = (el >> 6) * 16 + rsub;
;           bf16_t* cptr = Cb + (size_t)(brow + ai * HALF + rl0) * N + bcol + cch * 8;
;           const char* lptr = cst + rl0 * CROW + cch * 16;
; #pragma unroll
;           for (int i = 0; i < 8; ++i) {
;             typedef unsigned u32x4 __attribute__((ext_vector_type(4)));
;             u32x4 v = *(const u32x4*)(lptr + i * 2 * CROW);
;             __builtin_nontemporal_store(v, (u32x4*)cptr);
;             cptr += 2 * N;
;           }
;         }
;     ...
;     asm volatile("s_waitcnt vmcnt(0)" ::: "memory");
;     brow = nbrow;
;     bcol = nbcol;
	v_cvt_pk_bf16_f32 v33, v34, v35
	v_lshrrev_b32_e32 v65, 2, v64
	v_and_b32_e32 v66, 15, v64
	v_and_or_b32 v65, v65, 64, v66
	v_lshrrev_b32_e32 v66, 1, v64
	v_mad_u32_u24 v65, v65, s68, v143
	v_and_b32_e32 v66, 24, v66
	v_and_b32_e32 v64, 0xc0, v64
	v_add3_u32 v64, v65, v64, v66
	v_add_u32_e32 v50, 0x2000, v64
	v_add_u32_e32 v42, 0x4000, v64
	v_add_u32_e32 v34, 0x6000, v64
	v_cvt_pk_bf16_f32 v28, v28, v29
	v_cvt_pk_bf16_f32 v29, v30, v31
	v_cvt_pk_bf16_f32 v24, v24, v25
	v_cvt_pk_bf16_f32 v25, v26, v27
	v_cvt_pk_bf16_f32 v20, v20, v21
	v_cvt_pk_bf16_f32 v21, v22, v23
	v_cvt_pk_bf16_f32 v16, v16, v17
	v_cvt_pk_bf16_f32 v17, v18, v19
	v_cvt_pk_bf16_f32 v12, v12, v13
	v_cvt_pk_bf16_f32 v13, v14, v15
	v_cvt_pk_bf16_f32 v8, v8, v9
	v_cvt_pk_bf16_f32 v9, v10, v11
	v_cvt_pk_bf16_f32 v4, v4, v5
	v_cvt_pk_bf16_f32 v5, v6, v7
	v_cvt_pk_bf16_f32 v0, v0, v1
	v_cvt_pk_bf16_f32 v1, v2, v3
	ds_write2_b64 v64, v[60:61], v[56:57] offset1:4
	ds_write2_b64 v50, v[52:53], v[48:49] offset0:32 offset1:36
	ds_write2_b64 v42, v[44:45], v[40:41] offset0:64 offset1:68
	ds_write2_b64 v34, v[36:37], v[32:33] offset0:96 offset1:100
	ds_write2_b64 v64, v[28:29], v[24:25] offset0:32 offset1:36
	ds_write2_b64 v50, v[20:21], v[16:17] offset0:64 offset1:68
	ds_write2_b64 v42, v[12:13], v[8:9] offset0:96 offset1:100
	ds_write2_b64 v34, v[4:5], v[0:1] offset0:128 offset1:132
	v_mov_b32_e32 v0, v150
	s_waitcnt lgkmcnt(0)
	s_barrier
	s_mov_b32 s46, s54
	v_bfe_u32 v1, v0, 5, 1
	v_ashrrev_i32_e32 v2, 2, v0
	v_and_or_b32 v1, v2, -16, v1
	v_lshlrev_b32_e32 v0, 4, v0
	v_and_b32_e32 v132, 0x1f0, v0
	v_mul_lo_u32 v0, v1, s68
	v_add3_u32 v12, s66, v0, v132
	v_add_u32_e32 v4, s48, v1
	ds_read_b128 v[0:3], v12
	v_mad_i64_i32 v[4:5], s[44:45], v4, s69, v[72:73]
	v_lshl_add_u64 v[8:9], v[4:5], 0, v[132:133]
	ds_read_b128 v[4:7], v12 offset:1056
	s_waitcnt lgkmcnt(0)
	global_store_dwordx4 v[8:9], v[0:3], off nt
	s_mov_b32 s44, s52
	s_nop 0
	v_add_co_u32_e32 v0, vcc, s71, v8
	s_nop 1
	v_addc_co_u32_e32 v1, vcc, 0, v9, vcc
	global_store_dwordx4 v[0:1], v[4:7], off offset:1024 nt
	ds_read_b128 v[0:3], v12 offset:2112
	ds_read_b128 v[4:7], v12 offset:3168
	v_add_co_u32_e32 v10, vcc, s67, v8
	s_nop 1
	v_addc_co_u32_e32 v11, vcc, 0, v9, vcc
	s_waitcnt lgkmcnt(0)
	global_store_dwordx4 v[10:11], v[0:3], off offset:2048 nt
	s_nop 1
	v_add_co_u32_e32 v0, vcc, s72, v8
	s_nop 1
	v_addc_co_u32_e32 v1, vcc, 0, v9, vcc
	global_store_dwordx4 v[0:1], v[4:7], off offset:3072 nt
	ds_read_b128 v[0:3], v12 offset:4224
	ds_read_b128 v[4:7], v12 offset:5280
	v_add_co_u32_e32 v10, vcc, s73, v8
	s_nop 1
	v_addc_co_u32_e32 v11, vcc, 0, v9, vcc
	s_waitcnt lgkmcnt(0)
	global_store_dwordx4 v[10:11], v[0:3], off nt
	s_nop 1
	v_add_co_u32_e32 v0, vcc, s74, v8
	s_nop 1
	v_addc_co_u32_e32 v1, vcc, 0, v9, vcc
	global_store_dwordx4 v[0:1], v[4:7], off offset:1024 nt
	ds_read_b128 v[0:3], v12 offset:6336
	ds_read_b128 v[4:7], v12 offset:7392
	v_add_co_u32_e32 v10, vcc, 0x5b000, v8
	s_nop 1
	v_addc_co_u32_e32 v11, vcc, 0, v9, vcc
	s_waitcnt lgkmcnt(0)
	global_store_dwordx4 v[10:11], v[0:3], off offset:2048 nt
	s_nop 1
	v_add_co_u32_e32 v0, vcc, 0x6a000, v8
	s_nop 1
	v_addc_co_u32_e32 v1, vcc, 0, v9, vcc
	global_store_dwordx4 v[0:1], v[4:7], off offset:3072 nt
	s_waitcnt lgkmcnt(0)
	s_barrier
	s_waitcnt vmcnt(0)
	s_andn2_b64 vcc, exec, s[50:51]
	s_cbranch_vccz .LBB0_139

; #define WAIT_V(n) asm volatile("s_waitcnt vmcnt(" #n ")" ::: "memory")
; #define BAR __builtin_amdgcn_s_barrier()
; template <int MODE, int N>
; __device__ __forceinline__ void gemm_phase(const bf16_t* __restrict__ A, const bf16_t* __restrict__ Bt,
;                            bf16_t* __restrict__ Cb, float* __restrict__ Cf, const float* __restrict__ resid,
;                            float alpha) {
;     ...
;   for (int tile = blockIdx.x; tile < nwg; tile += gridDim.x) {
;     f32x4 acc[2][2][4][2] = {};
;     bf16x8 At[4][2], B0[2][2], B1[2][2];
;     if (wr == 1) BAR;
;     WAIT_V(4);
;     BAR;
;     STAGE(SB(1, 0), Bt, bcol, 1);
;     STAGE(SA(1, 0), A, brow, 1);
;     STAGE(SB(1, 1), Bt, bcol + HALF, 1);
;     WAIT_V(6);
;     BAR;
.LBB0_133:
	s_ashr_i32 s47, s46, 31
	s_lshl_b64 s[50:51], s[46:47], 13
	s_add_u32 s48, s8, s50
	s_addc_u32 s49, s9, s51
	v_lshl_add_u64 v[0:1], s[48:49], 0, v[134:135]
	s_add_i32 s54, s58, 0x18000
	s_ashr_i32 s45, s44, 31
	v_lshl_add_u64 v[0:1], v[0:1], 0, s[16:17]
	s_mov_b32 m0, s54
	s_add_i32 s55, s58, 0x1a000
	s_lshl_b64 s[52:53], s[44:45], 13
	s_waitcnt vmcnt(4)
	s_barrier
	global_load_lds_dwordx4 v[0:1], off
	v_lshl_add_u64 v[0:1], s[48:49], 0, v[136:137]
	s_add_u32 s78, s19, s52
	v_lshl_add_u64 v[0:1], v[0:1], 0, s[16:17]
	s_mov_b32 m0, s55
	s_addc_u32 s79, s24, s53
	global_load_lds_dwordx4 v[0:1], off
	v_lshl_add_u64 v[0:1], s[78:79], 0, v[134:135]
	s_add_i32 s45, s58, 0x10000
	v_lshl_add_u64 v[0:1], v[0:1], 0, s[16:17]
	s_mov_b32 m0, s45
	s_mov_b32 s81, -2
	global_load_lds_dwordx4 v[0:1], off
	v_lshl_add_u64 v[0:1], s[78:79], 0, v[136:137]
	s_add_i32 s78, s58, 0x12000
	s_add_u32 s48, s48, 0x100000
	v_lshl_add_u64 v[0:1], v[0:1], 0, s[16:17]
	s_mov_b32 m0, s78
	s_addc_u32 s49, s49, 0
	global_load_lds_dwordx4 v[0:1], off
	v_lshl_add_u64 v[0:1], s[48:49], 0, v[134:135]
	s_add_i32 s79, s58, 0x1c000
	v_lshl_add_u64 v[0:1], v[0:1], 0, s[16:17]
	s_mov_b32 m0, s79
	s_add_i32 s80, s58, 0x1e000
	global_load_lds_dwordx4 v[0:1], off
	v_lshl_add_u64 v[0:1], s[48:49], 0, v[136:137]
	v_lshl_add_u64 v[0:1], v[0:1], 0, s[16:17]
	s_mov_b32 m0, s80
	s_mov_b64 s[48:49], s[8:9]
	global_load_lds_dwordx4 v[0:1], off
	s_waitcnt vmcnt(6)
	v_mov_b32_e32 v0, 0
	v_mov_b32_e32 v1, v0
	v_mov_b32_e32 v2, v0
	v_mov_b32_e32 v3, v0
	v_mov_b32_e32 v4, v0
	v_mov_b32_e32 v5, v0
	v_mov_b32_e32 v6, v0
	v_mov_b32_e32 v7, v0
	v_mov_b32_e32 v8, v0
	v_mov_b32_e32 v9, v0
	v_mov_b32_e32 v10, v0
	v_mov_b32_e32 v11, v0
	v_mov_b32_e32 v12, v0
	v_mov_b32_e32 v13, v0
	v_mov_b32_e32 v14, v0
	v_mov_b32_e32 v15, v0
	v_mov_b32_e32 v16, v0
	v_mov_b32_e32 v17, v0
	v_mov_b32_e32 v18, v0
	v_mov_b32_e32 v19, v0
	v_mov_b32_e32 v20, v0
	v_mov_b32_e32 v21, v0
	v_mov_b32_e32 v22, v0
	v_mov_b32_e32 v23, v0
	v_mov_b32_e32 v24, v0
	v_mov_b32_e32 v25, v0
	v_mov_b32_e32 v26, v0
	v_mov_b32_e32 v27, v0
	v_mov_b32_e32 v28, v0
	v_mov_b32_e32 v29, v0
	v_mov_b32_e32 v30, v0
	v_mov_b32_e32 v31, v0
	v_mov_b32_e32 v32, v0
	v_mov_b32_e32 v33, v0
	v_mov_b32_e32 v34, v0
	v_mov_b32_e32 v35, v0
	v_mov_b32_e32 v36, v0
	v_mov_b32_e32 v37, v0
	v_mov_b32_e32 v38, v0
	v_mov_b32_e32 v39, v0
	v_mov_b32_e32 v40, v0
	v_mov_b32_e32 v41, v0
	v_mov_b32_e32 v42, v0
	v_mov_b32_e32 v43, v0
	v_mov_b32_e32 v44, v0
	v_mov_b32_e32 v45, v0
	v_mov_b32_e32 v46, v0
	v_mov_b32_e32 v47, v0
	v_mov_b32_e32 v48, v0
	v_mov_b32_e32 v49, v0
	v_mov_b32_e32 v50, v0
	v_mov_b32_e32 v51, v0
	v_mov_b32_e32 v52, v0
	v_mov_b32_e32 v53, v0
	v_mov_b32_e32 v54, v0
	v_mov_b32_e32 v55, v0
	v_mov_b32_e32 v56, v0
	v_mov_b32_e32 v57, v0
	v_mov_b32_e32 v58, v0
	v_mov_b32_e32 v59, v0
	v_mov_b32_e32 v60, v0
	v_mov_b32_e32 v61, v0
	v_mov_b32_e32 v62, v0
	v_mov_b32_e32 v63, v0
	v_mov_b32_e32 v64, v0
	v_mov_b32_e32 v65, v0
	v_mov_b32_e32 v66, v0
	v_mov_b32_e32 v67, v0
	v_mov_b32_e32 v68, v0
	v_mov_b32_e32 v69, v0
	v_mov_b32_e32 v70, v0
	v_mov_b32_e32 v71, v0
	v_mov_b32_e32 v72, v0
	v_mov_b32_e32 v73, v0
	v_mov_b32_e32 v74, v0
	v_mov_b32_e32 v75, v0
	v_mov_b32_e32 v76, v0
	v_mov_b32_e32 v77, v0
	v_mov_b32_e32 v78, v0
	v_mov_b32_e32 v79, v0
	v_mov_b32_e32 v80, v0
	v_mov_b32_e32 v81, v0
	v_mov_b32_e32 v82, v0
	v_mov_b32_e32 v83, v0
	v_mov_b32_e32 v84, v0
	v_mov_b32_e32 v85, v0
	v_mov_b32_e32 v86, v0
	v_mov_b32_e32 v87, v0
	v_mov_b32_e32 v88, v0
	v_mov_b32_e32 v89, v0
	v_mov_b32_e32 v90, v0
	v_mov_b32_e32 v91, v0
	v_mov_b32_e32 v92, v0
	v_mov_b32_e32 v93, v0
	v_mov_b32_e32 v94, v0
	v_mov_b32_e32 v95, v0
	v_mov_b32_e32 v96, v0
	v_mov_b32_e32 v97, v0
	v_mov_b32_e32 v98, v0
	v_mov_b32_e32 v99, v0
	v_mov_b32_e32 v100, v0
	v_mov_b32_e32 v101, v0
	v_mov_b32_e32 v102, v0
	v_mov_b32_e32 v103, v0
	v_mov_b32_e32 v104, v0
	v_mov_b32_e32 v105, v0
	v_mov_b32_e32 v106, v0
	v_mov_b32_e32 v107, v0
	v_mov_b32_e32 v108, v0
	v_mov_b32_e32 v109, v0
	v_mov_b32_e32 v110, v0
	v_mov_b32_e32 v111, v0
	v_mov_b32_e32 v112, v0
	v_mov_b32_e32 v113, v0
	v_mov_b32_e32 v114, v0
	v_mov_b32_e32 v115, v0
	v_mov_b32_e32 v116, v0
	v_mov_b32_e32 v117, v0
	v_mov_b32_e32 v118, v0
	v_mov_b32_e32 v119, v0
	v_mov_b32_e32 v120, v0
	v_mov_b32_e32 v121, v0
	v_mov_b32_e32 v122, v0
	v_mov_b32_e32 v123, v0
	v_mov_b32_e32 v124, v0
	v_mov_b32_e32 v125, v0
	v_mov_b32_e32 v126, v0
	v_mov_b32_e32 v127, v0
	v_lshl_add_u64 v[142:143], v[138:139], 0, s[52:53]
	v_lshl_add_u64 v[144:145], v[140:141], 0, s[52:53]
	v_lshl_add_u64 v[146:147], v[138:139], 0, s[50:51]
	v_lshl_add_u64 v[148:149], v[140:141], 0, s[50:51]
	s_barrier

; __device__ __forceinline__ void attn_phase(const bf16_t* __restrict__ proj, const bf16_t* __restrict__ KC,
;                            const bf16_t* __restrict__ VCT, const bf16_t* __restrict__ VT,
;                            bf16_t* __restrict__ mixed) {
;     ...
;         const bf16_t* kc = KC + (size_t)(b * 4 + g) * 256 * 128;
;         const bf16_t* kp = kc + (size_t)krow0 * 128 + kch * 8;
;         uint4 ka0 = *(const uint4*)(kp), ka1 = *(const uint4*)(kp + 32 * 128);
;         uint4 kb0 = *(const uint4*)(kp + 64 * 128), kb1 = *(const uint4*)(kp + 64 * 128 + 32 * 128);
;         __syncthreads();
;         stage_write_k(Kt, krow0, kch, ka0, ka1);
;         stage_write_k(Kt + 64 * KT_STRIDE, krow0, kch, kb0, kb1);
;         if (ntile_c > 2) {
;           ka0 = *(const uint4*)(kp + 128 * 128); ka1 = *(const uint4*)(kp + 128 * 128 + 32 * 128);
;           kb0 = *(const uint4*)(kp + 192 * 128); kb1 = *(const uint4*)(kp + 192 * 128 + 32 * 128);
;           stage_write_k(Kt + 128 * KT_STRIDE, krow0, kch, ka0, ka1);
;           stage_write_k(Kt + 192 * KT_STRIDE, krow0, kch, kb0, kb1);
;         }
;         __syncthreads();
.LBB0_259:
	s_lshl_b32 s66, s71, 2
	v_or_b32_e32 v26, s66, v184
	v_mov_b64_e32 v[24:25], s[36:37]
	v_mad_u64_u32 v[200:201], s[12:13], v26, s81, v[24:25]
	v_mad_i32_i24 v201, v185, s81, v201
	v_lshlrev_b32_e32 v180, 1, v106
	v_lshl_add_u64 v[24:25], v[200:201], 0, v[180:181]
	v_mov_b32_e32 v105, v181
	v_lshl_add_u64 v[24:25], v[24:25], 0, v[104:105]
	v_lshl_add_u64 v[26:27], v[24:25], 0, s[40:41]
	v_add_co_u32_e32 v24, vcc, s47, v24
	s_nop 1
	v_addc_co_u32_e32 v25, vcc, 0, v25, vcc
	global_load_dwordx4 v[56:59], v[26:27], off offset:64
	global_load_dwordx4 v[52:55], v[26:27], off offset:128
	global_load_dwordx4 v[60:63], v[24:25], off
	global_load_dwordx4 v[44:47], v[26:27], off offset:192
	v_cndmask_b32_e64 v24, 0, 1, s[58:59]
	v_cmp_ne_u32_e64 s[12:13], 1, v24
	s_andn2_b64 vcc, exec, s[58:59]
	s_barrier
	s_waitcnt vmcnt(5)
	ds_write_b128 v218, v[16:19]
	ds_write_b128 v218, v[0:3] offset:8704
	ds_write_b128 v218, v[4:7] offset:17408
	ds_write_b128 v218, v[8:11] offset:26112
	s_cbranch_vccnz .LBB0_261
	global_load_dwordx4 v[24:27], v[112:113], off
	global_load_dwordx4 v[28:31], v[114:115], off
	global_load_dwordx4 v[32:35], v[116:117], off
	global_load_dwordx4 v[36:39], v[118:119], off
	s_waitcnt vmcnt(3)
	ds_write_b128 v218, v[24:27] offset:34816
	s_waitcnt vmcnt(2)
	ds_write_b128 v218, v[28:31] offset:43520
	s_waitcnt vmcnt(1)
	ds_write_b128 v218, v[32:35] offset:52224
	s_waitcnt vmcnt(0)
	ds_write_b128 v218, v[36:39] offset:60928

; __device__ __forceinline__ void attn_phase(const bf16_t* __restrict__ proj, const bf16_t* __restrict__ KC,
;                            const bf16_t* __restrict__ VCT, const bf16_t* __restrict__ VT,
;                            bf16_t* __restrict__ mixed) {
;     ...
;       int nval = ((tk + 1) >> 4) - 1;
;       if (nval < 0) nval = 0;
;     ...
;       float mx = -1e30f;
; #pragma unroll
;       for (int mt = 0; mt < 16; ++mt)
; #pragma unroll
;         for (int jj = 0; jj < 4; ++jj) {
;           int n = mt * 16 + quad * 4 + jj;
;           float x = (n < nval) ? sc[mt][jj] * SCL : -1e30f;
;           sc[mt][jj] = x;
;           mx = fmaxf(mx, x);
;         }
.LBB0_267:
	v_ashrrev_i32_e32 v44, 4, v105
	v_max_i32_e32 v44, 1, v44
	v_add_u32_e32 v59, -1, v44
	s_nop 4
	v_pk_mul_f32 v[44:45], v[102:103], s[42:43] op_sel_hi:[1,0]
	v_cmp_lt_u32_e32 vcc, v179, v59
	v_pk_mul_f32 v[46:47], v[98:99], s[42:43] op_sel_hi:[1,0]
	v_pk_mul_f32 v[42:43], v[42:43], s[42:43] op_sel_hi:[1,0]
	v_cndmask_b32_e32 v102, v214, v45, vcc
	v_cmp_lt_u32_e32 vcc, v192, v59
	v_pk_mul_f32 v[40:41], v[40:41], s[42:43] op_sel_hi:[1,0]
	v_pk_mul_f32 v[38:39], v[38:39], s[42:43] op_sel_hi:[1,0]
	v_cndmask_b32_e32 v103, v214, v44, vcc
	v_pk_mul_f32 v[44:45], v[100:101], s[42:43] op_sel_hi:[1,0]
	v_cmp_lt_u32_e32 vcc, v177, v59
	v_pk_mul_f32 v[36:37], v[36:37], s[42:43] op_sel_hi:[1,0]
	v_pk_mul_f32 v[34:35], v[34:35], s[42:43] op_sel_hi:[1,0]
	v_cndmask_b32_e32 v100, v214, v45, vcc
	v_cmp_lt_u32_e32 vcc, v178, v59
	v_pk_mul_f32 v[32:33], v[32:33], s[42:43] op_sel_hi:[1,0]
	v_pk_mul_f32 v[30:31], v[30:31], s[42:43] op_sel_hi:[1,0]
	v_cndmask_b32_e32 v101, v214, v44, vcc
	v_cmp_lt_u32_e32 vcc, v175, v59
	v_pk_mul_f32 v[28:29], v[28:29], s[42:43] op_sel_hi:[1,0]
	v_pk_mul_f32 v[26:27], v[26:27], s[42:43] op_sel_hi:[1,0]
	v_cndmask_b32_e32 v44, v214, v47, vcc
	v_cmp_lt_u32_e32 vcc, v176, v59
	v_pk_mul_f32 v[24:25], v[24:25], s[42:43] op_sel_hi:[1,0]
	s_nop 0
	v_cndmask_b32_e32 v98, v214, v46, vcc
	v_pk_mul_f32 v[46:47], v[96:97], s[42:43] op_sel_hi:[1,0]
	v_cmp_lt_u32_e32 vcc, v173, v59
	s_nop 1
	v_cndmask_b32_e32 v45, v214, v47, vcc
	v_cmp_lt_u32_e32 vcc, v174, v59
	s_nop 1
	v_cndmask_b32_e32 v96, v214, v46, vcc
	v_pk_mul_f32 v[46:47], v[94:95], s[42:43] op_sel_hi:[1,0]
	v_cmp_lt_u32_e32 vcc, v171, v59
	s_nop 1
	v_cndmask_b32_e32 v52, v214, v47, vcc
	v_cmp_lt_u32_e32 vcc, v172, v59
	s_nop 1
	v_cndmask_b32_e32 v94, v214, v46, vcc
	v_pk_mul_f32 v[46:47], v[92:93], s[42:43] op_sel_hi:[1,0]
	v_cmp_lt_u32_e32 vcc, v169, v59
	s_nop 1
	v_cndmask_b32_e32 v53, v214, v47, vcc
	v_cmp_lt_u32_e32 vcc, v170, v59
	s_nop 1
	v_cndmask_b32_e32 v92, v214, v46, vcc
	v_pk_mul_f32 v[46:47], v[66:67], s[42:43] op_sel_hi:[1,0]
	v_cmp_lt_u32_e32 vcc, v167, v59
	s_nop 1
	v_cndmask_b32_e32 v56, v214, v47, vcc
	v_cmp_lt_u32_e32 vcc, v168, v59
	s_nop 1
	v_cndmask_b32_e32 v93, v214, v46, vcc
	v_pk_mul_f32 v[46:47], v[64:65], s[42:43] op_sel_hi:[1,0]
	v_cmp_lt_u32_e32 vcc, v165, v59
	s_nop 1
	v_cndmask_b32_e32 v54, v214, v47, vcc
	v_cmp_lt_u32_e32 vcc, v166, v59
	s_nop 1
	v_cndmask_b32_e32 v57, v214, v46, vcc
	v_pk_mul_f32 v[46:47], v[90:91], s[42:43] op_sel_hi:[1,0]
	v_cmp_lt_u32_e32 vcc, v163, v59
	s_nop 1
	v_cndmask_b32_e32 v55, v214, v47, vcc
	v_cmp_lt_u32_e32 vcc, v164, v59
	s_nop 1
	v_cndmask_b32_e32 v60, v214, v46, vcc
	v_pk_mul_f32 v[46:47], v[88:89], s[42:43] op_sel_hi:[1,0]
	v_cmp_lt_u32_e32 vcc, v161, v59
	s_nop 1
	v_cndmask_b32_e32 v58, v214, v47, vcc
	v_cmp_lt_u32_e32 vcc, v162, v59
	s_nop 1
	v_cndmask_b32_e32 v61, v214, v46, vcc
	v_pk_mul_f32 v[46:47], v[86:87], s[42:43] op_sel_hi:[1,0]
	v_cmp_lt_u32_e32 vcc, v159, v59
	s_nop 1
	v_cndmask_b32_e32 v64, v214, v47, vcc
	v_cmp_lt_u32_e32 vcc, v160, v59
	s_nop 1
	v_cndmask_b32_e32 v90, v214, v46, vcc
	v_pk_mul_f32 v[46:47], v[84:85], s[42:43] op_sel_hi:[1,0]
	v_cmp_lt_u32_e32 vcc, v157, v59
	s_nop 1
	v_cndmask_b32_e32 v62, v214, v47, vcc
	v_cmp_lt_u32_e32 vcc, v158, v59
	s_nop 1
	v_cndmask_b32_e32 v65, v214, v46, vcc
	v_pk_mul_f32 v[46:47], v[82:83], s[42:43] op_sel_hi:[1,0]
	v_cmp_lt_u32_e32 vcc, v155, v59
	s_nop 1
	v_cndmask_b32_e32 v63, v214, v47, vcc
	v_cmp_lt_u32_e32 vcc, v156, v59
	s_nop 1
	v_cndmask_b32_e32 v91, v214, v46, vcc
	v_pk_mul_f32 v[46:47], v[80:81], s[42:43] op_sel_hi:[1,0]
	v_cmp_lt_u32_e32 vcc, v153, v59
	s_nop 1
	v_cndmask_b32_e32 v66, v214, v47, vcc
	v_cmp_lt_u32_e32 vcc, v154, v59
	s_nop 1
	v_cndmask_b32_e32 v95, v214, v46, vcc
	v_pk_mul_f32 v[46:47], v[78:79], s[42:43] op_sel_hi:[1,0]
	v_cmp_lt_u32_e32 vcc, v151, v59
	s_nop 1
	v_cndmask_b32_e32 v67, v214, v47, vcc
	v_cmp_lt_u32_e32 vcc, v152, v59
	s_nop 1
	v_cndmask_b32_e32 v97, v214, v46, vcc
	v_pk_mul_f32 v[46:47], v[76:77], s[42:43] op_sel_hi:[1,0]
	v_cmp_lt_u32_e32 vcc, v149, v59
	s_nop 1
	v_cndmask_b32_e32 v99, v214, v47, vcc
	v_cmp_lt_u32_e32 vcc, v150, v59
	s_nop 1
	v_cndmask_b32_e32 v105, v214, v46, vcc
	v_pk_mul_f32 v[46:47], v[74:75], s[42:43] op_sel_hi:[1,0]
	v_cmp_lt_u32_e32 vcc, v147, v59
	s_nop 1
	v_cndmask_b32_e32 v76, v214, v47, vcc
	v_cmp_lt_u32_e32 vcc, v148, v59
	s_nop 1
	v_cndmask_b32_e32 v190, v214, v46, vcc
	v_pk_mul_f32 v[46:47], v[72:73], s[42:43] op_sel_hi:[1,0]
	v_cmp_lt_u32_e32 vcc, v145, v59
	s_nop 1
	v_cndmask_b32_e32 v72, v214, v47, vcc
	v_cmp_lt_u32_e32 vcc, v146, v59
	s_nop 1
	v_cndmask_b32_e32 v73, v214, v46, vcc
	v_pk_mul_f32 v[46:47], v[70:71], s[42:43] op_sel_hi:[1,0]
	v_cmp_lt_u32_e32 vcc, v143, v59
	s_nop 1
	v_cndmask_b32_e32 v70, v214, v47, vcc
	v_cmp_lt_u32_e32 vcc, v144, v59
	s_nop 1
	v_cndmask_b32_e32 v71, v214, v46, vcc
	v_pk_mul_f32 v[46:47], v[68:69], s[42:43] op_sel_hi:[1,0]
	v_cmp_lt_u32_e32 vcc, v141, v59
	s_nop 1
	v_cndmask_b32_e32 v68, v214, v47, vcc
	v_cmp_lt_u32_e32 vcc, v142, v59
	s_nop 1
	v_cndmask_b32_e32 v69, v214, v46, vcc
	v_pk_mul_f32 v[46:47], v[50:51], s[42:43] op_sel_hi:[1,0]
	v_cmp_lt_u32_e32 vcc, v139, v59
	s_nop 1
	v_cndmask_b32_e32 v50, v214, v47, vcc
	v_cmp_lt_u32_e32 vcc, v140, v59
	s_nop 1
	v_cndmask_b32_e32 v51, v214, v46, vcc
	v_pk_mul_f32 v[46:47], v[48:49], s[42:43] op_sel_hi:[1,0]
	v_cmp_lt_u32_e32 vcc, v137, v59
	s_nop 1
	v_cndmask_b32_e32 v74, v214, v47, vcc
	v_cmp_lt_u32_e32 vcc, v138, v59
	s_nop 1
	v_cndmask_b32_e32 v75, v214, v46, vcc
	v_cmp_lt_u32_e32 vcc, v135, v59
	s_nop 1
	v_cndmask_b32_e32 v43, v214, v43, vcc
	v_cmp_lt_u32_e32 vcc, v136, v59
; __device__ __forceinline__ void attn_phase(const bf16_t* __restrict__ proj, const bf16_t* __restrict__ KC,
;                            const bf16_t* __restrict__ VCT, const bf16_t* __restrict__ VT,
;                            bf16_t* __restrict__ mixed) {
;     ...
;       float mx = -1e30f;
; #pragma unroll
;       for (int mt = 0; mt < 16; ++mt)
; #pragma unroll
;         for (int jj = 0; jj < 4; ++jj) {
;           int n = mt * 16 + quad * 4 + jj;
;           float x = (n < nval) ? sc[mt][jj] * SCL : -1e30f;
;           sc[mt][jj] = x;
;           mx = fmaxf(mx, x);
;         }
;       mx = quad_max(mx);
;       float lsum = 0.f;
; #pragma unroll
;       for (int mt = 0; mt < 16; ++mt)
; #pragma unroll
;         for (int jj = 0; jj < 4; ++jj) {
;           float x = sc[mt][jj];
;           float p = (x > -1e29f) ? __builtin_amdgcn_exp2f(x - mx) : 0.f;
;           sc[mt][jj] = p;
;           lsum += p;
;         }
;       lsum = quad_sum(lsum);
	s_nop 1
	v_cndmask_b32_e32 v42, v214, v42, vcc
	v_cmp_lt_u32_e32 vcc, v133, v59
	s_nop 1
	v_cndmask_b32_e32 v41, v214, v41, vcc
	v_cmp_lt_u32_e32 vcc, v134, v59
	s_nop 1
	v_cndmask_b32_e32 v40, v214, v40, vcc
	v_cmp_lt_u32_e32 vcc, v131, v59
	s_nop 1
	v_cndmask_b32_e32 v39, v214, v39, vcc
	v_cmp_lt_u32_e32 vcc, v132, v59
	s_nop 1
	v_cndmask_b32_e32 v38, v214, v38, vcc
	v_cmp_lt_u32_e32 vcc, v129, v59
	s_nop 1
	v_cndmask_b32_e32 v37, v214, v37, vcc
	v_cmp_lt_u32_e32 vcc, v130, v59
	s_nop 1
	v_cndmask_b32_e32 v36, v214, v36, vcc
	v_cmp_lt_u32_e32 vcc, v127, v59
	s_nop 1
	v_cndmask_b32_e32 v35, v214, v35, vcc
	v_cmp_lt_u32_e32 vcc, v128, v59
	s_nop 1
	v_cndmask_b32_e32 v34, v214, v34, vcc
	v_cmp_lt_u32_e32 vcc, v125, v59
	s_nop 1
	v_cndmask_b32_e32 v33, v214, v33, vcc
	v_cmp_lt_u32_e32 vcc, v126, v59
	s_nop 1
	v_cndmask_b32_e32 v32, v214, v32, vcc
	v_cmp_lt_u32_e32 vcc, v123, v59
	s_nop 1
	v_cndmask_b32_e32 v31, v214, v31, vcc
	v_cmp_lt_u32_e32 vcc, v124, v59
	s_nop 1
	v_cndmask_b32_e32 v30, v214, v30, vcc
	v_cmp_lt_u32_e32 vcc, v121, v59
	s_nop 1
	v_cndmask_b32_e32 v29, v214, v29, vcc
	v_cmp_lt_u32_e32 vcc, v122, v59
	s_nop 1
	v_cndmask_b32_e32 v28, v214, v28, vcc
	v_cmp_lt_u32_e32 vcc, v111, v59
	s_nop 1
	v_cndmask_b32_e32 v46, v214, v27, vcc
	v_cmp_lt_u32_e32 vcc, v120, v59
	s_nop 1
	v_cndmask_b32_e32 v47, v214, v26, vcc
	v_cmp_lt_u32_e32 vcc, v107, v59
	s_nop 1
	v_cndmask_b32_e32 v25, v214, v25, vcc
	v_cmp_lt_u32_e32 vcc, v188, v59
	s_nop 1
	v_cndmask_b32_e32 v24, v214, v24, vcc
	v_max3_f32 v26, v24, s82, v25
	v_max3_f32 v26, v26, v47, v46
	v_max3_f32 v26, v26, v28, v29
	v_max3_f32 v26, v26, v30, v31
	v_max3_f32 v26, v26, v32, v33
	v_max3_f32 v26, v26, v34, v35
	v_max3_f32 v26, v26, v36, v37
	v_max3_f32 v26, v26, v38, v39
	v_max3_f32 v26, v26, v40, v41
	v_max3_f32 v26, v26, v42, v43
	v_max3_f32 v26, v26, v75, v74
	v_max3_f32 v26, v26, v51, v50
	v_max3_f32 v26, v26, v69, v68
	v_max3_f32 v26, v26, v71, v70
	v_max3_f32 v26, v26, v73, v72
	v_max3_f32 v26, v26, v190, v76
	v_max3_f32 v26, v26, v105, v99
	v_max3_f32 v26, v26, v97, v67
	v_max3_f32 v26, v26, v95, v66
	v_max3_f32 v26, v26, v91, v63
	v_max3_f32 v26, v26, v65, v62
	v_max3_f32 v26, v26, v90, v64
	v_max3_f32 v26, v26, v61, v58
	v_max3_f32 v26, v26, v60, v55
	v_max3_f32 v26, v26, v57, v54
	v_max3_f32 v26, v26, v93, v56
	v_max3_f32 v26, v26, v92, v53
	v_max3_f32 v26, v26, v94, v52
	v_max3_f32 v26, v26, v96, v45
	v_max3_f32 v26, v26, v98, v44
	v_max3_f32 v26, v26, v101, v100
	v_max3_f32 v26, v26, v103, v102
	v_mov_b32_e32 v27, v26
	s_nop 1
	v_permlane16_swap_b32_e32 v26, v27
	v_max_f32_e32 v27, v27, v27
	v_max_f32_e32 v26, v26, v26
	v_max_f32_e32 v26, v26, v27
	v_mov_b32_e32 v27, v26
	s_nop 1
	v_permlane32_swap_b32_e32 v26, v27
	v_max_f32_e32 v27, v27, v27
	v_max_f32_e32 v26, v26, v26
	v_max_f32_e32 v191, v26, v27
	v_sub_f32_e32 v26, v25, v191
	v_exp_f32_e32 v26, v26
	v_sub_f32_e32 v27, v24, v191
	v_exp_f32_e32 v48, v27
	v_cmp_lt_f32_e32 vcc, s83, v25
	v_sub_f32_e32 v25, v47, v191
	v_exp_f32_e32 v49, v25
	v_cndmask_b32_e32 v27, 0, v26, vcc
	v_cmp_lt_f32_e32 vcc, s83, v24
	s_nop 1
	v_cndmask_b32_e32 v26, 0, v48, vcc
	v_add_f32_e32 v24, 0, v26
	v_add_f32_e32 v48, v27, v24
	v_sub_f32_e32 v24, v46, v191
	v_exp_f32_e32 v24, v24
	v_cmp_lt_f32_e32 vcc, s83, v46
	s_nop 1
	v_cndmask_b32_e32 v25, 0, v24, vcc
	v_cmp_lt_f32_e32 vcc, s83, v47
	v_sub_f32_e32 v47, v29, v191
	v_exp_f32_e32 v47, v47
	v_cndmask_b32_e32 v24, 0, v49, vcc
	v_add_f32_e32 v46, v24, v48
	v_sub_f32_e32 v48, v28, v191
	v_exp_f32_e32 v48, v48
	v_cmp_lt_f32_e32 vcc, s83, v29
	v_add_f32_e32 v46, v25, v46
	s_nop 0
	v_cndmask_b32_e32 v29, 0, v47, vcc
	v_cmp_lt_f32_e32 vcc, s83, v28
	v_sub_f32_e32 v47, v31, v191
	v_exp_f32_e32 v47, v47
	v_cndmask_b32_e32 v28, 0, v48, vcc
	v_sub_f32_e32 v48, v30, v191
	v_exp_f32_e32 v48, v48
	v_cmp_lt_f32_e32 vcc, s83, v31
	v_add_f32_e32 v46, v28, v46
	v_add_f32_e32 v46, v29, v46
	v_cndmask_b32_e32 v31, 0, v47, vcc
	v_cmp_lt_f32_e32 vcc, s83, v30
	v_sub_f32_e32 v47, v33, v191
	v_exp_f32_e32 v47, v47
	v_cndmask_b32_e32 v30, 0, v48, vcc
	v_sub_f32_e32 v48, v32, v191
	v_exp_f32_e32 v48, v48
	v_cmp_lt_f32_e32 vcc, s83, v33
	v_add_f32_e32 v46, v30, v46
	v_add_f32_e32 v46, v31, v46
	v_cndmask_b32_e32 v33, 0, v47, vcc
	v_cmp_lt_f32_e32 vcc, s83, v32
	v_sub_f32_e32 v47, v35, v191
	v_exp_f32_e32 v47, v47
	v_cndmask_b32_e32 v32, 0, v48, vcc
	v_sub_f32_e32 v48, v34, v191
	v_exp_f32_e32 v48, v48
	v_cmp_lt_f32_e32 vcc, s83, v35
	v_add_f32_e32 v46, v32, v46
	v_add_f32_e32 v46, v33, v46
	v_cndmask_b32_e32 v35, 0, v47, vcc
	v_cmp_lt_f32_e32 vcc, s83, v34
	v_sub_f32_e32 v47, v36, v191
	v_exp_f32_e32 v49, v47
	v_cndmask_b32_e32 v34, 0, v48, vcc
	v_add_f32_e32 v46, v34, v46
	v_add_f32_e32 v48, v35, v46
	v_sub_f32_e32 v46, v37, v191
	v_exp_f32_e32 v46, v46
	v_cmp_lt_f32_e32 vcc, s83, v37
	v_sub_f32_e32 v37, v39, v191
	v_exp_f32_e32 v37, v37
	v_cndmask_b32_e32 v47, 0, v46, vcc
	v_cmp_lt_f32_e32 vcc, s83, v36
	s_nop 1
	v_cndmask_b32_e32 v46, 0, v49, vcc
	v_add_f32_e32 v36, v46, v48
	v_sub_f32_e32 v48, v38, v191
	v_cmp_lt_f32_e32 vcc, s83, v39
	v_exp_f32_e32 v48, v48
	v_add_f32_e32 v36, v47, v36
	v_cndmask_b32_e32 v49, 0, v37, vcc
	v_sub_f32_e32 v37, v41, v191
	v_cmp_lt_f32_e32 vcc, s83, v38
	v_exp_f32_e32 v37, v37
	v_sub_f32_e32 v38, v40, v191
	v_exp_f32_e32 v38, v38
	v_cndmask_b32_e32 v48, 0, v48, vcc
	v_cmp_lt_f32_e32 vcc, s83, v41
	v_add_f32_e32 v36, v48, v36
	v_add_f32_e32 v36, v49, v36
	v_cndmask_b32_e32 v87, 0, v37, vcc
	v_cmp_lt_f32_e32 vcc, s83, v40
	v_sub_f32_e32 v37, v43, v191
	v_exp_f32_e32 v37, v37
	v_cndmask_b32_e32 v86, 0, v38, vcc
	v_sub_f32_e32 v38, v42, v191
	v_exp_f32_e32 v38, v38
	v_cmp_lt_f32_e32 vcc, s83, v43
; __device__ __forceinline__ void attn_phase(const bf16_t* __restrict__ proj, const bf16_t* __restrict__ KC,
;                            const bf16_t* __restrict__ VCT, const bf16_t* __restrict__ VT,
;                            bf16_t* __restrict__ mixed) {
;     ...
;       float lsum = 0.f;
; #pragma unroll
;       for (int mt = 0; mt < 16; ++mt)
; #pragma unroll
;         for (int jj = 0; jj < 4; ++jj) {
;           float x = sc[mt][jj];
;           float p = (x > -1e29f) ? __builtin_amdgcn_exp2f(x - mx) : 0.f;
;           sc[mt][jj] = p;
;           lsum += p;
;         }
;       lsum = quad_sum(lsum);
	v_add_f32_e32 v36, v86, v36
	v_add_f32_e32 v36, v87, v36
	v_cndmask_b32_e32 v89, 0, v37, vcc
	v_cmp_lt_f32_e32 vcc, s83, v42
	v_sub_f32_e32 v37, v74, v191
	v_exp_f32_e32 v37, v37
	v_cndmask_b32_e32 v88, 0, v38, vcc
	v_sub_f32_e32 v38, v75, v191
	v_exp_f32_e32 v38, v38
	v_cmp_lt_f32_e32 vcc, s83, v74
	v_add_f32_e32 v36, v88, v36
	v_add_f32_e32 v36, v89, v36
	v_cndmask_b32_e32 v83, 0, v37, vcc
	v_cmp_lt_f32_e32 vcc, s83, v75
	v_sub_f32_e32 v37, v50, v191
	v_exp_f32_e32 v37, v37
	v_cndmask_b32_e32 v82, 0, v38, vcc
	v_sub_f32_e32 v38, v51, v191
	v_exp_f32_e32 v38, v38
	v_cmp_lt_f32_e32 vcc, s83, v50
	v_add_f32_e32 v36, v82, v36
	v_add_f32_e32 v36, v83, v36
	v_cndmask_b32_e32 v85, 0, v37, vcc
	v_cmp_lt_f32_e32 vcc, s83, v51
	v_sub_f32_e32 v37, v68, v191
	v_exp_f32_e32 v37, v37
	v_cndmask_b32_e32 v84, 0, v38, vcc
	v_sub_f32_e32 v38, v69, v191
	v_exp_f32_e32 v38, v38
	v_cmp_lt_f32_e32 vcc, s83, v68
	v_add_f32_e32 v36, v84, v36
	v_add_f32_e32 v36, v85, v36
	v_cndmask_b32_e32 v79, 0, v37, vcc
	v_cmp_lt_f32_e32 vcc, s83, v69
	v_sub_f32_e32 v37, v70, v191
	v_exp_f32_e32 v37, v37
	v_cndmask_b32_e32 v78, 0, v38, vcc
	v_sub_f32_e32 v38, v71, v191
	v_exp_f32_e32 v38, v38
	v_cmp_lt_f32_e32 vcc, s83, v70
	v_add_f32_e32 v36, v78, v36
	v_add_f32_e32 v36, v79, v36
	v_cndmask_b32_e32 v81, 0, v37, vcc
	v_cmp_lt_f32_e32 vcc, s83, v71
	v_sub_f32_e32 v37, v72, v191
	v_exp_f32_e32 v37, v37
	v_cndmask_b32_e32 v80, 0, v38, vcc
	v_sub_f32_e32 v38, v73, v191
	v_exp_f32_e32 v38, v38
	v_cmp_lt_f32_e32 vcc, s83, v72
	v_add_f32_e32 v36, v80, v36
	v_add_f32_e32 v36, v81, v36
	v_cndmask_b32_e32 v75, 0, v37, vcc
	v_cmp_lt_f32_e32 vcc, s83, v73
	v_sub_f32_e32 v37, v76, v191
	v_exp_f32_e32 v37, v37
	v_cndmask_b32_e32 v74, 0, v38, vcc
	v_sub_f32_e32 v38, v190, v191
	v_exp_f32_e32 v38, v38
	v_cmp_lt_f32_e32 vcc, s83, v76
	v_add_f32_e32 v36, v74, v36
	v_add_f32_e32 v36, v75, v36
	v_cndmask_b32_e32 v77, 0, v37, vcc
	v_cmp_lt_f32_e32 vcc, s83, v190
	v_sub_f32_e32 v37, v99, v191
	v_exp_f32_e32 v37, v37
	v_cndmask_b32_e32 v76, 0, v38, vcc
	v_sub_f32_e32 v38, v105, v191
	v_exp_f32_e32 v38, v38
	v_cmp_lt_f32_e32 vcc, s83, v99
	v_add_f32_e32 v36, v76, v36
	v_add_f32_e32 v36, v77, v36
	v_cndmask_b32_e32 v71, 0, v37, vcc
	v_cmp_lt_f32_e32 vcc, s83, v105
	v_sub_f32_e32 v37, v67, v191
	v_exp_f32_e32 v37, v37
	v_cndmask_b32_e32 v70, 0, v38, vcc
	v_sub_f32_e32 v38, v97, v191
	v_exp_f32_e32 v38, v38
	v_cmp_lt_f32_e32 vcc, s83, v67
	v_add_f32_e32 v36, v70, v36
	v_add_f32_e32 v36, v71, v36
	v_cndmask_b32_e32 v73, 0, v37, vcc
	v_cmp_lt_f32_e32 vcc, s83, v97
	v_sub_f32_e32 v37, v66, v191
	v_exp_f32_e32 v37, v37
	v_cndmask_b32_e32 v72, 0, v38, vcc
	v_sub_f32_e32 v38, v95, v191
	v_exp_f32_e32 v38, v38
	v_cmp_lt_f32_e32 vcc, s83, v66
	v_add_f32_e32 v36, v72, v36
	v_add_f32_e32 v36, v73, v36
	v_cndmask_b32_e32 v67, 0, v37, vcc
	v_cmp_lt_f32_e32 vcc, s83, v95
	v_sub_f32_e32 v37, v63, v191
	v_exp_f32_e32 v37, v37
	v_cndmask_b32_e32 v66, 0, v38, vcc
	v_sub_f32_e32 v38, v91, v191
	v_exp_f32_e32 v38, v38
	v_cmp_lt_f32_e32 vcc, s83, v63
	v_add_f32_e32 v36, v66, v36
	v_add_f32_e32 v36, v67, v36
	v_cndmask_b32_e32 v69, 0, v37, vcc
	v_cmp_lt_f32_e32 vcc, s83, v91
	v_sub_f32_e32 v37, v62, v191
	v_exp_f32_e32 v37, v37
	v_cndmask_b32_e32 v68, 0, v38, vcc
	v_sub_f32_e32 v38, v65, v191
	v_exp_f32_e32 v38, v38
	v_cmp_lt_f32_e32 vcc, s83, v62
	v_add_f32_e32 v36, v68, v36
	v_add_f32_e32 v36, v69, v36
	v_cndmask_b32_e32 v63, 0, v37, vcc
	v_cmp_lt_f32_e32 vcc, s83, v65
	v_sub_f32_e32 v37, v64, v191
	v_exp_f32_e32 v37, v37
	v_cndmask_b32_e32 v62, 0, v38, vcc
	v_sub_f32_e32 v38, v90, v191
	v_exp_f32_e32 v38, v38
	v_cmp_lt_f32_e32 vcc, s83, v64
	v_add_f32_e32 v36, v62, v36
	v_add_f32_e32 v36, v63, v36
	v_cndmask_b32_e32 v65, 0, v37, vcc
	v_cmp_lt_f32_e32 vcc, s83, v90
	v_sub_f32_e32 v37, v58, v191
	v_exp_f32_e32 v37, v37
	v_cndmask_b32_e32 v64, 0, v38, vcc
	v_sub_f32_e32 v38, v61, v191
	v_exp_f32_e32 v38, v38
	v_cmp_lt_f32_e32 vcc, s83, v58
	v_add_f32_e32 v36, v64, v36
	v_add_f32_e32 v36, v65, v36
	v_cndmask_b32_e32 v59, 0, v37, vcc
	v_cmp_lt_f32_e32 vcc, s83, v61
	v_sub_f32_e32 v37, v55, v191
	v_exp_f32_e32 v37, v37
	v_cndmask_b32_e32 v58, 0, v38, vcc
	v_sub_f32_e32 v38, v60, v191
	v_exp_f32_e32 v38, v38
	v_cmp_lt_f32_e32 vcc, s83, v55
	v_add_f32_e32 v36, v58, v36
	v_add_f32_e32 v36, v59, v36
	v_cndmask_b32_e32 v61, 0, v37, vcc
	v_cmp_lt_f32_e32 vcc, s83, v60
	v_sub_f32_e32 v37, v54, v191
	v_exp_f32_e32 v37, v37
	v_cndmask_b32_e32 v60, 0, v38, vcc
	v_sub_f32_e32 v38, v57, v191
	v_exp_f32_e32 v38, v38
	v_cmp_lt_f32_e32 vcc, s83, v54
	v_add_f32_e32 v36, v60, v36
	v_add_f32_e32 v36, v61, v36
	v_cndmask_b32_e32 v55, 0, v37, vcc
	v_cmp_lt_f32_e32 vcc, s83, v57
	v_sub_f32_e32 v37, v56, v191
	v_exp_f32_e32 v37, v37
	v_cndmask_b32_e32 v54, 0, v38, vcc
	v_sub_f32_e32 v38, v93, v191
	v_exp_f32_e32 v38, v38
	v_cmp_lt_f32_e32 vcc, s83, v56
	v_add_f32_e32 v36, v54, v36
	v_add_f32_e32 v36, v55, v36
	v_cndmask_b32_e32 v57, 0, v37, vcc
	v_cmp_lt_f32_e32 vcc, s83, v93
	v_sub_f32_e32 v37, v53, v191
	v_exp_f32_e32 v37, v37
	v_cndmask_b32_e32 v56, 0, v38, vcc
	v_sub_f32_e32 v38, v92, v191
	v_exp_f32_e32 v38, v38
	v_cmp_lt_f32_e32 vcc, s83, v53
	v_add_f32_e32 v36, v56, v36
	v_add_f32_e32 v36, v57, v36
	v_cndmask_b32_e32 v51, 0, v37, vcc
	v_cmp_lt_f32_e32 vcc, s83, v92
	v_sub_f32_e32 v37, v52, v191
	v_exp_f32_e32 v37, v37
	v_cndmask_b32_e32 v50, 0, v38, vcc
	v_sub_f32_e32 v38, v94, v191
	v_exp_f32_e32 v38, v38
	v_cmp_lt_f32_e32 vcc, s83, v52
	v_add_f32_e32 v36, v50, v36
	v_add_f32_e32 v36, v51, v36
	v_cndmask_b32_e32 v53, 0, v37, vcc
	v_cmp_lt_f32_e32 vcc, s83, v94
	v_sub_f32_e32 v37, v45, v191
	v_exp_f32_e32 v37, v37
	v_cndmask_b32_e32 v52, 0, v38, vcc
; __device__ __forceinline__ void attn_phase(const bf16_t* __restrict__ proj, const bf16_t* __restrict__ KC,
;                            const bf16_t* __restrict__ VCT, const bf16_t* __restrict__ VT,
;                            bf16_t* __restrict__ mixed) {
;     ...
;       lsum = quad_sum(lsum);
;       const float inv = lsum > 0.f ? 1.0f / lsum : 0.f;
;       float rot_prev = 0.f;
; #pragma unroll
;       for (int mt = 0; mt < 16; ++mt) {
;         sc[mt][0] *= inv; sc[mt][1] *= inv; sc[mt][2] *= inv; sc[mt][3] *= inv;
;         float own = (sc[mt][0] + sc[mt][1]) + (sc[mt][2] + sc[mt][3]);
;         float rot = __shfl(sc[mt][3], (lane + 48) & 63);
;         float prev = (quad == 0) ? rot_prev : rot;
;         rot_prev = rot;
;         float ps = own + prev;
;         ps += __shfl_xor(ps, 1);
;         ps += __shfl_xor(ps, 2);
;         if (r == 0) pslc[(w * 8 + qs * 4 + tl) * 64 + mt * 4 + quad] = ps;
;       }
	v_sub_f32_e32 v38, v96, v191
	v_exp_f32_e32 v38, v38
	v_cmp_lt_f32_e32 vcc, s83, v45
	v_add_f32_e32 v36, v52, v36
	v_add_f32_e32 v36, v53, v36
	v_cndmask_b32_e32 v43, 0, v37, vcc
	v_cmp_lt_f32_e32 vcc, s83, v96
	v_sub_f32_e32 v37, v44, v191
	v_exp_f32_e32 v37, v37
	v_cndmask_b32_e32 v42, 0, v38, vcc
	v_sub_f32_e32 v38, v98, v191
	v_exp_f32_e32 v38, v38
	v_cmp_lt_f32_e32 vcc, s83, v44
	v_add_f32_e32 v36, v42, v36
	v_add_f32_e32 v36, v43, v36
	v_cndmask_b32_e32 v45, 0, v37, vcc
	v_cmp_lt_f32_e32 vcc, s83, v98
	v_sub_f32_e32 v37, v101, v191
	v_exp_f32_e32 v39, v37
	v_cndmask_b32_e32 v44, 0, v38, vcc
	v_add_f32_e32 v36, v44, v36
	v_add_f32_e32 v38, v45, v36
	v_sub_f32_e32 v36, v100, v191
	v_exp_f32_e32 v36, v36
	v_cmp_lt_f32_e32 vcc, s83, v100
	s_nop 1
	v_cndmask_b32_e32 v37, 0, v36, vcc
	v_cmp_lt_f32_e32 vcc, s83, v101
	s_nop 1
	v_cndmask_b32_e32 v36, 0, v39, vcc
	v_add_f32_e32 v38, v36, v38
	v_add_f32_e32 v40, v37, v38
	v_sub_f32_e32 v38, v102, v191
	v_exp_f32_e32 v38, v38
	v_sub_f32_e32 v39, v103, v191
	v_exp_f32_e32 v41, v39
	v_cmp_lt_f32_e32 vcc, s83, v102
	s_nop 1
	v_cndmask_b32_e32 v39, 0, v38, vcc
	v_cmp_lt_f32_e32 vcc, s83, v103
	s_nop 1
	v_cndmask_b32_e32 v38, 0, v41, vcc
	v_add_f32_e32 v40, v38, v40
	v_add_f32_e32 v40, v39, v40
	v_mov_b32_e32 v41, v40
	s_nop 1
	v_permlane16_swap_b32_e32 v40, v41
	v_add_f32_e32 v40, v40, v41
	v_mov_b32_e32 v41, v40
	s_nop 1
	v_permlane32_swap_b32_e32 v40, v41
	v_add_f32_e32 v40, v40, v41
	v_div_scale_f32 v41, vcc, v40, v40, 1.0
	v_rcp_f32_e32 v90, v41
	s_nop 0
	v_fma_f32 v91, -v41, v90, 1.0
	v_fmac_f32_e32 v90, v91, v90
	v_div_scale_f32 v91, vcc, 1.0, v40, 1.0
	v_mul_f32_e32 v92, v91, v90
	v_fma_f32 v93, -v41, v92, v91
	v_fmac_f32_e32 v92, v93, v90
	v_fma_f32 v41, -v41, v92, v91
	v_div_fmas_f32 v41, v41, v90, v92
	v_div_fixup_f32 v41, v41, v40, 1.0
	v_cmp_lt_f32_e32 vcc, 0, v40
	v_or_b32_e32 v92, s66, v226
	v_lshlrev_b32_e32 v92, 8, v92
	v_cndmask_b32_e32 v40, 0, v41, vcc
	v_pk_mul_f32 v[24:25], v[40:41], v[24:25] op_sel_hi:[0,1]
	ds_bpermute_b32 v91, v219, v25
	v_pk_mul_f32 v[26:27], v[40:41], v[26:27] op_sel_hi:[0,1]
	v_add_f32_e32 v41, v24, v25
	v_add_f32_e32 v90, v26, v27
	v_add_f32_e32 v41, v90, v41
	s_waitcnt lgkmcnt(0)
	v_cndmask_b32_e64 v90, v91, 0, s[8:9]
	v_add_f32_e32 v41, v90, v41
	s_nop 1
	v_add_f32_dpp v90, v41, v41 quad_perm:[1,0,3,2] row_mask:0xf bank_mask:0xf
	v_add_u32_e32 v105, v222, v92
	s_nop 1
	v_add_f32_dpp v41, v90, v90 quad_perm:[2,3,0,1] row_mask:0xf bank_mask:0xf
	s_and_saveexec_b64 s[66:67], s[10:11]
	s_cbranch_execz .LBB0_269
	ds_write_b32 v105, v41
.LBB0_269:
	s_or_b64 exec, exec, s[66:67]
	v_mov_b32_e32 v41, v40
	v_pk_mul_f32 v[28:29], v[40:41], v[28:29]
	v_pk_mul_f32 v[30:31], v[40:41], v[30:31]
	v_add_f32_e32 v92, v28, v29
	s_waitcnt lgkmcnt(0)
	v_add_f32_e32 v90, v30, v31
	v_add_f32_e32 v92, v92, v90
	ds_bpermute_b32 v90, v219, v31
	s_waitcnt lgkmcnt(0)
	v_cndmask_b32_e64 v91, v90, v91, s[8:9]
	v_add_f32_e32 v91, v92, v91
	s_nop 1
	v_add_f32_dpp v92, v91, v91 quad_perm:[1,0,3,2] row_mask:0xf bank_mask:0xf
	s_nop 1
	v_add_f32_dpp v91, v92, v92 quad_perm:[2,3,0,1] row_mask:0xf bank_mask:0xf
	s_and_saveexec_b64 s[66:67], s[10:11]
	s_cbranch_execz .LBB0_271
	ds_write_b32 v105, v91 offset:16
.LBB0_271:
	s_or_b64 exec, exec, s[66:67]
	v_pk_mul_f32 v[32:33], v[40:41], v[32:33]
	v_pk_mul_f32 v[34:35], v[40:41], v[34:35]
	s_waitcnt lgkmcnt(0)
	v_add_f32_e32 v92, v32, v33
	v_add_f32_e32 v91, v34, v35
	v_add_f32_e32 v92, v92, v91
	ds_bpermute_b32 v91, v219, v35
	s_waitcnt lgkmcnt(0)
	v_cndmask_b32_e64 v90, v91, v90, s[8:9]
	v_add_f32_e32 v90, v92, v90
	s_nop 1
	v_add_f32_dpp v92, v90, v90 quad_perm:[1,0,3,2] row_mask:0xf bank_mask:0xf
	s_nop 1
	v_add_f32_dpp v90, v92, v92 quad_perm:[2,3,0,1] row_mask:0xf bank_mask:0xf
	s_and_saveexec_b64 s[66:67], s[10:11]
	s_cbranch_execz .LBB0_273
	ds_write_b32 v105, v90 offset:32
.LBB0_273:
	s_or_b64 exec, exec, s[66:67]
	v_pk_mul_f32 v[46:47], v[40:41], v[46:47]
	v_pk_mul_f32 v[48:49], v[40:41], v[48:49]
	s_waitcnt lgkmcnt(0)
	v_add_f32_e32 v92, v46, v47
	v_add_f32_e32 v90, v48, v49
	v_add_f32_e32 v92, v92, v90
	ds_bpermute_b32 v90, v219, v49
	s_waitcnt lgkmcnt(0)
	v_cndmask_b32_e64 v91, v90, v91, s[8:9]
	v_add_f32_e32 v91, v92, v91
	s_nop 1
	v_add_f32_dpp v92, v91, v91 quad_perm:[1,0,3,2] row_mask:0xf bank_mask:0xf
	s_nop 1
	v_add_f32_dpp v91, v92, v92 quad_perm:[2,3,0,1] row_mask:0xf bank_mask:0xf
	s_and_saveexec_b64 s[66:67], s[10:11]
	s_cbranch_execz .LBB0_275
	ds_write_b32 v105, v91 offset:48
.LBB0_275:
	s_or_b64 exec, exec, s[66:67]
	v_pk_mul_f32 v[96:97], v[40:41], v[86:87]
	v_pk_mul_f32 v[98:99], v[40:41], v[88:89]
	v_add_f32_e32 v87, v96, v97
	v_add_f32_e32 v86, v98, v99
	v_add_f32_e32 v87, v87, v86
	ds_bpermute_b32 v86, v219, v99
	s_waitcnt lgkmcnt(0)
	v_cndmask_b32_e64 v88, v86, v90, s[8:9]
	v_add_f32_e32 v87, v87, v88
	s_nop 1
	v_add_f32_dpp v88, v87, v87 quad_perm:[1,0,3,2] row_mask:0xf bank_mask:0xf
	s_nop 1
	v_add_f32_dpp v87, v88, v88 quad_perm:[2,3,0,1] row_mask:0xf bank_mask:0xf
	s_and_saveexec_b64 s[66:67], s[10:11]
	s_cbranch_execz .LBB0_277
	ds_write_b32 v105, v87 offset:64
.LBB0_277:
	s_or_b64 exec, exec, s[66:67]
	v_pk_mul_f32 v[100:101], v[40:41], v[82:83]
	v_pk_mul_f32 v[102:103], v[40:41], v[84:85]
	v_add_f32_e32 v83, v100, v101
	v_add_f32_e32 v82, v102, v103
	v_add_f32_e32 v83, v83, v82
	ds_bpermute_b32 v82, v219, v103
	s_waitcnt lgkmcnt(0)
	v_cndmask_b32_e64 v84, v82, v86, s[8:9]
	v_add_f32_e32 v83, v83, v84
	s_nop 1
	v_add_f32_dpp v84, v83, v83 quad_perm:[1,0,3,2] row_mask:0xf bank_mask:0xf
	s_nop 1
	v_add_f32_dpp v83, v84, v84 quad_perm:[2,3,0,1] row_mask:0xf bank_mask:0xf
	s_and_saveexec_b64 s[66:67], s[10:11]
	s_cbranch_execz .LBB0_279
	ds_write_b32 v105, v83 offset:80
; __device__ __forceinline__ void attn_phase(const bf16_t* __restrict__ proj, const bf16_t* __restrict__ KC,
;                            const bf16_t* __restrict__ VCT, const bf16_t* __restrict__ VT,
;                            bf16_t* __restrict__ mixed) {
;     ...
;       float rot_prev = 0.f;
; #pragma unroll
;       for (int mt = 0; mt < 16; ++mt) {
;         sc[mt][0] *= inv; sc[mt][1] *= inv; sc[mt][2] *= inv; sc[mt][3] *= inv;
;         float own = (sc[mt][0] + sc[mt][1]) + (sc[mt][2] + sc[mt][3]);
;         float rot = __shfl(sc[mt][3], (lane + 48) & 63);
;         float prev = (quad == 0) ? rot_prev : rot;
;         rot_prev = rot;
;         float ps = own + prev;
;         ps += __shfl_xor(ps, 1);
;         ps += __shfl_xor(ps, 2);
;         if (r == 0) pslc[(w * 8 + qs * 4 + tl) * 64 + mt * 4 + quad] = ps;
;       }
.LBB0_279:
	s_or_b64 exec, exec, s[66:67]
	v_pk_mul_f32 v[190:191], v[40:41], v[78:79]
	v_pk_mul_f32 v[202:203], v[40:41], v[80:81]
	v_add_f32_e32 v79, v190, v191
	v_add_f32_e32 v78, v202, v203
	v_add_f32_e32 v79, v79, v78
	ds_bpermute_b32 v78, v219, v203
	s_waitcnt lgkmcnt(0)
	v_cndmask_b32_e64 v80, v78, v82, s[8:9]
	v_add_f32_e32 v79, v79, v80
	s_nop 1
	v_add_f32_dpp v80, v79, v79 quad_perm:[1,0,3,2] row_mask:0xf bank_mask:0xf
	s_nop 1
	v_add_f32_dpp v79, v80, v80 quad_perm:[2,3,0,1] row_mask:0xf bank_mask:0xf
	s_and_saveexec_b64 s[66:67], s[10:11]
	s_cbranch_execz .LBB0_281
	ds_write_b32 v105, v79 offset:96
.LBB0_281:
	s_or_b64 exec, exec, s[66:67]
	v_pk_mul_f32 v[204:205], v[40:41], v[74:75]
	v_pk_mul_f32 v[206:207], v[40:41], v[76:77]
	v_add_f32_e32 v75, v204, v205
	v_add_f32_e32 v74, v206, v207
	v_add_f32_e32 v75, v75, v74
	ds_bpermute_b32 v74, v219, v207
	s_waitcnt lgkmcnt(0)
	v_cndmask_b32_e64 v76, v74, v78, s[8:9]
	v_add_f32_e32 v75, v75, v76
	s_nop 1
	v_add_f32_dpp v76, v75, v75 quad_perm:[1,0,3,2] row_mask:0xf bank_mask:0xf
	s_nop 1
	v_add_f32_dpp v75, v76, v76 quad_perm:[2,3,0,1] row_mask:0xf bank_mask:0xf
	s_and_saveexec_b64 s[66:67], s[10:11]
	s_cbranch_execz .LBB0_283
	ds_write_b32 v105, v75 offset:112
.LBB0_283:
	s_or_b64 exec, exec, s[66:67]
	v_pk_mul_f32 v[84:85], v[40:41], v[70:71]
	v_pk_mul_f32 v[90:91], v[40:41], v[72:73]
	v_add_f32_e32 v71, v84, v85
	v_add_f32_e32 v70, v90, v91
	v_add_f32_e32 v71, v71, v70
	ds_bpermute_b32 v70, v219, v91
	s_waitcnt lgkmcnt(0)
	v_cndmask_b32_e64 v72, v70, v74, s[8:9]
	v_add_f32_e32 v71, v71, v72
	s_nop 1
	v_add_f32_dpp v72, v71, v71 quad_perm:[1,0,3,2] row_mask:0xf bank_mask:0xf
	s_nop 1
	v_add_f32_dpp v71, v72, v72 quad_perm:[2,3,0,1] row_mask:0xf bank_mask:0xf
	s_and_saveexec_b64 s[66:67], s[10:11]
	s_cbranch_execz .LBB0_285
	ds_write_b32 v105, v71 offset:128
.LBB0_285:
	s_or_b64 exec, exec, s[66:67]
	v_pk_mul_f32 v[92:93], v[40:41], v[66:67]
	v_pk_mul_f32 v[94:95], v[40:41], v[68:69]
	v_add_f32_e32 v67, v92, v93
	v_add_f32_e32 v66, v94, v95
	v_add_f32_e32 v67, v67, v66
	ds_bpermute_b32 v66, v219, v95
	s_waitcnt lgkmcnt(0)
	v_cndmask_b32_e64 v68, v66, v70, s[8:9]
	v_add_f32_e32 v67, v67, v68
	s_nop 1
	v_add_f32_dpp v68, v67, v67 quad_perm:[1,0,3,2] row_mask:0xf bank_mask:0xf
	s_nop 1
	v_add_f32_dpp v67, v68, v68 quad_perm:[2,3,0,1] row_mask:0xf bank_mask:0xf
	s_and_saveexec_b64 s[66:67], s[10:11]
	s_cbranch_execz .LBB0_287
	ds_write_b32 v105, v67 offset:144
.LBB0_287:
	s_or_b64 exec, exec, s[66:67]
	v_pk_mul_f32 v[70:71], v[40:41], v[62:63]
	v_pk_mul_f32 v[76:77], v[40:41], v[64:65]
	v_add_f32_e32 v63, v70, v71
	v_add_f32_e32 v62, v76, v77
	v_add_f32_e32 v63, v63, v62
	ds_bpermute_b32 v62, v219, v77
	s_waitcnt lgkmcnt(0)
	v_cndmask_b32_e64 v64, v62, v66, s[8:9]
	v_add_f32_e32 v63, v63, v64
	s_nop 1
	v_add_f32_dpp v64, v63, v63 quad_perm:[1,0,3,2] row_mask:0xf bank_mask:0xf
	s_nop 1
	v_add_f32_dpp v63, v64, v64 quad_perm:[2,3,0,1] row_mask:0xf bank_mask:0xf
	s_and_saveexec_b64 s[66:67], s[10:11]
	s_cbranch_execz .LBB0_289
	ds_write_b32 v105, v63 offset:160
.LBB0_289:
	s_or_b64 exec, exec, s[66:67]
	v_pk_mul_f32 v[80:81], v[40:41], v[58:59]
	v_pk_mul_f32 v[86:87], v[40:41], v[60:61]
	v_add_f32_e32 v59, v80, v81
	v_add_f32_e32 v58, v86, v87
	v_add_f32_e32 v59, v59, v58
	ds_bpermute_b32 v58, v219, v87
	s_waitcnt lgkmcnt(0)
	v_cndmask_b32_e64 v60, v58, v62, s[8:9]
	v_add_f32_e32 v59, v59, v60
	s_nop 1
	v_add_f32_dpp v60, v59, v59 quad_perm:[1,0,3,2] row_mask:0xf bank_mask:0xf
	s_nop 1
	v_add_f32_dpp v59, v60, v60 quad_perm:[2,3,0,1] row_mask:0xf bank_mask:0xf
	s_and_saveexec_b64 s[66:67], s[10:11]
	s_cbranch_execz .LBB0_291
	ds_write_b32 v105, v59 offset:176
.LBB0_291:
	s_or_b64 exec, exec, s[66:67]
	v_pk_mul_f32 v[72:73], v[40:41], v[54:55]
	v_pk_mul_f32 v[78:79], v[40:41], v[56:57]
	v_add_f32_e32 v55, v72, v73
	v_add_f32_e32 v54, v78, v79
	v_add_f32_e32 v55, v55, v54
	ds_bpermute_b32 v54, v219, v79
	s_waitcnt lgkmcnt(0)
	v_cndmask_b32_e64 v56, v54, v58, s[8:9]
	v_add_f32_e32 v55, v55, v56
	s_nop 1
	v_add_f32_dpp v56, v55, v55 quad_perm:[1,0,3,2] row_mask:0xf bank_mask:0xf
	s_nop 1
	v_add_f32_dpp v55, v56, v56 quad_perm:[2,3,0,1] row_mask:0xf bank_mask:0xf
	s_and_saveexec_b64 s[66:67], s[10:11]
	s_cbranch_execz .LBB0_293
	ds_write_b32 v105, v55 offset:192
.LBB0_293:
	s_or_b64 exec, exec, s[66:67]
	v_pk_mul_f32 v[82:83], v[40:41], v[50:51]
	v_pk_mul_f32 v[88:89], v[40:41], v[52:53]
	v_add_f32_e32 v51, v82, v83
	v_add_f32_e32 v50, v88, v89
	v_add_f32_e32 v51, v51, v50
	ds_bpermute_b32 v50, v219, v89
	s_waitcnt lgkmcnt(0)
	v_cndmask_b32_e64 v52, v50, v54, s[8:9]
	v_add_f32_e32 v51, v51, v52
	s_nop 1
	v_add_f32_dpp v52, v51, v51 quad_perm:[1,0,3,2] row_mask:0xf bank_mask:0xf
	s_nop 1
	v_add_f32_dpp v51, v52, v52 quad_perm:[2,3,0,1] row_mask:0xf bank_mask:0xf
	s_and_saveexec_b64 s[66:67], s[10:11]
	s_cbranch_execz .LBB0_295
	ds_write_b32 v105, v51 offset:208
.LBB0_295:
	s_or_b64 exec, exec, s[66:67]
	v_pk_mul_f32 v[64:65], v[40:41], v[42:43]
	v_pk_mul_f32 v[66:67], v[40:41], v[44:45]
	v_add_f32_e32 v43, v64, v65
	v_add_f32_e32 v42, v66, v67
	v_add_f32_e32 v43, v43, v42
	ds_bpermute_b32 v42, v219, v67
	s_waitcnt lgkmcnt(0)
	v_cndmask_b32_e64 v44, v42, v50, s[8:9]
	v_add_f32_e32 v43, v43, v44
	s_nop 1
	v_add_f32_dpp v44, v43, v43 quad_perm:[1,0,3,2] row_mask:0xf bank_mask:0xf
	s_nop 1
	v_add_f32_dpp v43, v44, v44 quad_perm:[2,3,0,1] row_mask:0xf bank_mask:0xf
	s_and_saveexec_b64 s[66:67], s[10:11]
	s_cbranch_execz .LBB0_297
	ds_write_b32 v105, v43 offset:224
.LBB0_297:
	s_or_b64 exec, exec, s[66:67]
	v_pk_mul_f32 v[68:69], v[40:41], v[36:37]
	v_pk_mul_f32 v[74:75], v[40:41], v[38:39]
	v_add_f32_e32 v37, v68, v69
	v_add_f32_e32 v36, v74, v75
	v_add_f32_e32 v36, v37, v36
	ds_bpermute_b32 v37, v219, v75
	s_waitcnt lgkmcnt(0)
	v_cndmask_b32_e64 v37, v37, v42, s[8:9]
	v_add_f32_e32 v36, v36, v37
	s_nop 1
	v_add_f32_dpp v37, v36, v36 quad_perm:[1,0,3,2] row_mask:0xf bank_mask:0xf
	s_nop 1
	v_add_f32_dpp v36, v37, v37 quad_perm:[2,3,0,1] row_mask:0xf bank_mask:0xf
	s_and_saveexec_b64 s[66:67], s[10:11]
	s_cbranch_execz .LBB0_299
	ds_write_b32 v105, v36 offset:240

; __device__ __forceinline__ void attn_phase(const bf16_t* __restrict__ proj, const bf16_t* __restrict__ KC,
;                            const bf16_t* __restrict__ VCT, const bf16_t* __restrict__ VT,
;                            bf16_t* __restrict__ mixed) {
;     ...
;     unsigned long long mymask[2] = {0ull, 0ull}, wunion = 0ull;
;     {
;       const int cur = ttile;
;       if (cur < 16) {
;         const unsigned long long m = (2ull << cur) - 1ull;
;         mymask[0] = m;
;         mymask[1] = m;
;         wunion = m;
;       } else {
;         unsigned long long mm0 = 0ull, mm1 = 0ull;
; #pragma nounroll
;         for (int t8 = 0; t8 < 8; ++t8) {
;           const int J = lane;
;           const float psv = pslc[(w * 8 + t8) * 64 + J];
;           const bool valid = J <= cur;
;           const bool forced = (J == 0) || (valid && (J > cur - 2));
;           const float score = forced ? 1e9f : (valid ? psv : -1.0f);
;           const int sbits = __float_as_int(score);
;           int cnt = 0;
; #pragma unroll 8
;           for (int i = 0; i < 64; ++i) {
;             const float si = __int_as_float(__builtin_amdgcn_readlane(sbits, i));
;             cnt += ((si > score) || (si == score && i < J)) ? 1 : 0;
;           }
;           const unsigned long long m = __ballot(cnt < 16);
;           const bool mine = (tl == (t8 & 3));
;           if (mine && (t8 < 4)) mm0 = m;
;           if (mine && (t8 >= 4)) mm1 = m;
;           wunion |= m;
;         }
;         mymask[0] = mm0;
;         mymask[1] = mm1;
;       }
.LBB0_311:
	s_cmp_lt_u32 s96, 16
	s_waitcnt lgkmcnt(0)
	s_barrier
	s_cbranch_scc1 .LBB0_317
	s_add_i32 s10, s96, -2
	v_cmp_ge_u32_e32 vcc, s96, v183
	v_cmp_lt_i32_e64 s[10:11], s10, v183
	v_cmp_eq_u32_e64 s[58:59], 0, v183
	s_and_b64 s[10:11], vcc, s[10:11]
	v_lshl_add_u32 v0, v183, 2, s79
	s_or_b64 s[58:59], s[58:59], s[10:11]
	v_lshl_add_u32 v24, s25, 8, v0
	ds_read_b32 v16, v24 offset:0
	ds_read_b32 v17, v24 offset:256
	ds_read_b32 v18, v24 offset:512
	ds_read_b32 v19, v24 offset:768
	ds_read_b32 v20, v24 offset:1024
	ds_read_b32 v21, v24 offset:1280
	ds_read_b32 v22, v24 offset:1536
	ds_read_b32 v23, v24 offset:1792
	v_mov_b64_e32 v[160:161], 0
	s_mov_b64 s[16:17], 0
	v_mov_b64_e32 v[162:163], 0
	s_add_i32 s101, s96, 2
	s_and_b32 s101, s101, -2
	s_waitcnt lgkmcnt(0)
	v_cndmask_b32_e32 v16, -1.0, v16, vcc
	v_cndmask_b32_e32 v17, -1.0, v17, vcc
	v_cndmask_b32_e32 v18, -1.0, v18, vcc
	v_cndmask_b32_e32 v19, -1.0, v19, vcc
	v_cndmask_b32_e32 v20, -1.0, v20, vcc
	v_cndmask_b32_e32 v21, -1.0, v21, vcc
	v_cndmask_b32_e32 v22, -1.0, v22, vcc
	v_cndmask_b32_e32 v23, -1.0, v23, vcc
	v_cndmask_b32_e64 v16, v16, v215, s[58:59]
	v_cndmask_b32_e64 v17, v17, v215, s[58:59]
	v_cndmask_b32_e64 v18, v18, v215, s[58:59]
	v_cndmask_b32_e64 v19, v19, v215, s[58:59]
	v_cndmask_b32_e64 v20, v20, v215, s[58:59]
	v_cndmask_b32_e64 v21, v21, v215, s[58:59]
	v_cndmask_b32_e64 v22, v22, v215, s[58:59]
	v_cndmask_b32_e64 v23, v23, v215, s[58:59]
	v_xor_b32_e32 v1, 0x80000000, v16
	v_sub_u32_e32 v0, 63, v183
	v_xor_b32_e32 v3, 0x80000000, v17
	v_sub_u32_e32 v2, 63, v183
	v_xor_b32_e32 v5, 0x80000000, v18
	v_sub_u32_e32 v4, 63, v183
	v_xor_b32_e32 v7, 0x80000000, v19
	v_sub_u32_e32 v6, 63, v183
	v_xor_b32_e32 v9, 0x80000000, v20
	v_sub_u32_e32 v8, 63, v183
	v_xor_b32_e32 v11, 0x80000000, v21
	v_sub_u32_e32 v10, 63, v183
	v_xor_b32_e32 v13, 0x80000000, v22
	v_sub_u32_e32 v12, 63, v183
	v_xor_b32_e32 v15, 0x80000000, v23
	v_sub_u32_e32 v14, 63, v183
	v_mov_b32_e32 v24, 0
	v_mov_b32_e32 v25, 0
	v_mov_b32_e32 v26, 0
	v_mov_b32_e32 v27, 0
	v_mov_b32_e32 v28, 0
	v_mov_b32_e32 v29, 0
	v_mov_b32_e32 v30, 0
	v_mov_b32_e32 v31, 0
	s_mov_b32 s100, 0
.Ltk0_p0:
	s_sub_i32 s8, 63, s100
	s_sub_i32 s10, 63, s100
	s_sub_i32 s12, 63, s100
	s_sub_i32 s14, 63, s100
	v_readlane_b32 s9, v1, s100
	v_readlane_b32 s11, v3, s100
	v_readlane_b32 s13, v5, s100
	v_readlane_b32 s15, v7, s100
	v_cmp_gt_u64_e32 vcc, s[8:9], v[0:1]
	v_cmp_gt_u64_e64 s[58:59], s[10:11], v[2:3]
	v_cmp_gt_u64_e64 s[98:99], s[12:13], v[4:5]
	v_addc_co_u32_e64 v24, vcc, 0, v24, vcc
	v_cmp_gt_u64_e32 vcc, s[14:15], v[6:7]
	v_addc_co_u32_e64 v25, s[58:59], 0, v25, s[58:59]
	v_addc_co_u32_e64 v26, s[98:99], 0, v26, s[98:99]
	v_addc_co_u32_e64 v27, vcc, 0, v27, vcc
	s_add_i32 s100, s100, 1
	s_sub_i32 s8, 63, s100
	s_sub_i32 s10, 63, s100
	s_sub_i32 s12, 63, s100
	s_sub_i32 s14, 63, s100
	v_readlane_b32 s9, v1, s100
	v_readlane_b32 s11, v3, s100
	v_readlane_b32 s13, v5, s100
	v_readlane_b32 s15, v7, s100
	v_cmp_gt_u64_e32 vcc, s[8:9], v[0:1]
	v_cmp_gt_u64_e64 s[58:59], s[10:11], v[2:3]
	v_cmp_gt_u64_e64 s[98:99], s[12:13], v[4:5]
	v_addc_co_u32_e64 v24, vcc, 0, v24, vcc
	v_cmp_gt_u64_e32 vcc, s[14:15], v[6:7]
	v_addc_co_u32_e64 v25, s[58:59], 0, v25, s[58:59]
	v_addc_co_u32_e64 v26, s[98:99], 0, v26, s[98:99]
	v_addc_co_u32_e64 v27, vcc, 0, v27, vcc
	s_add_i32 s100, s100, 1
	s_cmp_lt_u32 s100, s101
	s_cbranch_scc1 .Ltk0_p0
	s_mov_b32 s100, 0
.Ltk0_p1:
	s_sub_i32 s8, 63, s100
	s_sub_i32 s10, 63, s100
	s_sub_i32 s12, 63, s100
	s_sub_i32 s14, 63, s100
	v_readlane_b32 s9, v9, s100
	v_readlane_b32 s11, v11, s100
	v_readlane_b32 s13, v13, s100
	v_readlane_b32 s15, v15, s100
	v_cmp_gt_u64_e32 vcc, s[8:9], v[8:9]
	v_cmp_gt_u64_e64 s[58:59], s[10:11], v[10:11]
	v_cmp_gt_u64_e64 s[98:99], s[12:13], v[12:13]
	v_addc_co_u32_e64 v28, vcc, 0, v28, vcc
	v_cmp_gt_u64_e32 vcc, s[14:15], v[14:15]
	v_addc_co_u32_e64 v29, s[58:59], 0, v29, s[58:59]
	v_addc_co_u32_e64 v30, s[98:99], 0, v30, s[98:99]
	v_addc_co_u32_e64 v31, vcc, 0, v31, vcc
	s_add_i32 s100, s100, 1
	s_sub_i32 s8, 63, s100
	s_sub_i32 s10, 63, s100
	s_sub_i32 s12, 63, s100
	s_sub_i32 s14, 63, s100
	v_readlane_b32 s9, v9, s100
	v_readlane_b32 s11, v11, s100
	v_readlane_b32 s13, v13, s100
	v_readlane_b32 s15, v15, s100
	v_cmp_gt_u64_e32 vcc, s[8:9], v[8:9]
	v_cmp_gt_u64_e64 s[58:59], s[10:11], v[10:11]
	v_cmp_gt_u64_e64 s[98:99], s[12:13], v[12:13]
	v_addc_co_u32_e64 v28, vcc, 0, v28, vcc
	v_cmp_gt_u64_e32 vcc, s[14:15], v[14:15]
	v_addc_co_u32_e64 v29, s[58:59], 0, v29, s[58:59]
	v_addc_co_u32_e64 v30, s[98:99], 0, v30, s[98:99]
	v_addc_co_u32_e64 v31, vcc, 0, v31, vcc
	s_add_i32 s100, s100, 1
	s_cmp_lt_u32 s100, s101
	s_cbranch_scc1 .Ltk0_p1
	v_cmp_gt_u32_e64 s[10:11], 16, v24
	v_cmp_eq_u32_e64 s[12:13], 0, v193
	s_nop 1
	v_mov_b32_e32 v16, s10
	v_mov_b32_e32 v17, s11
	s_or_b64 s[16:17], s[16:17], s[10:11]
	v_cndmask_b32_e64 v162, v162, v16, s[12:13]
	v_cndmask_b32_e64 v163, v163, v17, s[12:13]
	v_cmp_gt_u32_e64 s[10:11], 16, v25
	v_cmp_eq_u32_e64 s[12:13], 1, v193
	s_nop 1
	v_mov_b32_e32 v16, s10
	v_mov_b32_e32 v17, s11
	s_or_b64 s[16:17], s[16:17], s[10:11]
	v_cndmask_b32_e64 v162, v162, v16, s[12:13]
	v_cndmask_b32_e64 v163, v163, v17, s[12:13]
	v_cmp_gt_u32_e64 s[10:11], 16, v26
	v_cmp_eq_u32_e64 s[12:13], 2, v193
	s_nop 1
	v_mov_b32_e32 v16, s10
	v_mov_b32_e32 v17, s11
	s_or_b64 s[16:17], s[16:17], s[10:11]
	v_cndmask_b32_e64 v162, v162, v16, s[12:13]
	v_cndmask_b32_e64 v163, v163, v17, s[12:13]
	v_cmp_gt_u32_e64 s[10:11], 16, v27
	v_cmp_eq_u32_e64 s[12:13], 3, v193
	s_nop 1
	v_mov_b32_e32 v16, s10
	v_mov_b32_e32 v17, s11
	s_or_b64 s[16:17], s[16:17], s[10:11]
	v_cndmask_b32_e64 v162, v162, v16, s[12:13]
	v_cndmask_b32_e64 v163, v163, v17, s[12:13]
	v_cmp_gt_u32_e64 s[10:11], 16, v28
	v_cmp_eq_u32_e64 s[12:13], 0, v193
	s_nop 1
	v_mov_b32_e32 v16, s10
	v_mov_b32_e32 v17, s11
	s_or_b64 s[16:17], s[16:17], s[10:11]
	v_cndmask_b32_e64 v160, v160, v16, s[12:13]
	v_cndmask_b32_e64 v161, v161, v17, s[12:13]
	v_cmp_gt_u32_e64 s[10:11], 16, v29
	v_cmp_eq_u32_e64 s[12:13], 1, v193
	s_nop 1
	v_mov_b32_e32 v16, s10
	v_mov_b32_e32 v17, s11
	s_or_b64 s[16:17], s[16:17], s[10:11]
	v_cndmask_b32_e64 v160, v160, v16, s[12:13]
	v_cndmask_b32_e64 v161, v161, v17, s[12:13]
	v_cmp_gt_u32_e64 s[10:11], 16, v30
	v_cmp_eq_u32_e64 s[12:13], 2, v193
	s_nop 1
	v_mov_b32_e32 v16, s10
	v_mov_b32_e32 v17, s11
	s_or_b64 s[16:17], s[16:17], s[10:11]
	v_cndmask_b32_e64 v160, v160, v16, s[12:13]
	v_cndmask_b32_e64 v161, v161, v17, s[12:13]
	v_cmp_gt_u32_e64 s[10:11], 16, v31
	v_cmp_eq_u32_e64 s[12:13], 3, v193
	s_nop 1
	v_mov_b32_e32 v16, s10
	v_mov_b32_e32 v17, s11
	s_or_b64 s[16:17], s[16:17], s[10:11]
	v_cndmask_b32_e64 v160, v160, v16, s[12:13]
	v_cndmask_b32_e64 v161, v161, v17, s[12:13]
	s_branch .LBB0_319

; #define WAIT_L(n) asm volatile("s_waitcnt lgkmcnt(" #n ")" ::: "memory")
; #define BAR __builtin_amdgcn_s_barrier()
; template <int MODE, int N>
; __device__ __forceinline__ void gemm_phase(const bf16_t* __restrict__ A, const bf16_t* __restrict__ Bt,
;                            bf16_t* __restrict__ Cb, float* __restrict__ Cf, const float* __restrict__ resid,
;                            float alpha) {
;     ...
; #pragma unroll
;       for (int ai = 0; ai < 2; ++ai) {
;         {
;           int el0 = gtid;
;           asm volatile("" : "+v"(el0));
;           char* lb = cst + (((el0 >> 8) & 1) * 64 + (el0 & 15)) * CROW + (((el0 >> 6) & 3) * 32 + ((el0 >> 4) & 3) * 4) * 2;
;           for (int bj = 0; bj < 2; ++bj)
;             for (int m = 0; m < 4; ++m)
;               for (int n = 0; n < 2; ++n) {
;                 f32x4 v = acc[ai][bj][m][n];
;                 uint2 o;
;                 o.x = pack2(v[0], v[1]);
;                 o.y = pack2(v[2], v[3]);
;                 *(uint2*)(lb + m * 16 * CROW + bj * HALF * 2 + n * 32) = o;
;               }
;         }
;         WAIT_L(0);
;         BAR;
;         asm volatile("" ::: "memory");
;         {
;           int el = gtid;
;           asm volatile("" : "+v"(el));
;           const int rsub = (el >> 5) & 1, cch = el & 31, rl0 = (el >> 6) * 16 + rsub;
;           bf16_t* cptr = Cb + (size_t)(brow + ai * HALF + rl0) * N + bcol + cch * 8;
;           const char* lptr = cst + rl0 * CROW + cch * 16;
; #pragma unroll
;           for (int i = 0; i < 8; ++i) {
;             typedef unsigned u32x4 __attribute__((ext_vector_type(4)));
;             u32x4 v = *(const u32x4*)(lptr + i * 2 * CROW);
;             __builtin_nontemporal_store(v, (u32x4*)cptr);
;             cptr += 2 * N;
;           }
;         }
;         WAIT_L(0);
;         BAR;
;         asm volatile("" ::: "memory");
.LBB0_484:
	v_mov_b32_e32 v132, v150
	v_cvt_pk_bf16_f32 v92, v92, v93
	v_lshrrev_b32_e32 v142, 2, v132
	v_and_b32_e32 v143, 15, v132
	v_and_or_b32 v142, v142, 64, v143
	v_mov_b32_e32 v143, s69
	v_lshrrev_b32_e32 v144, 1, v132
	v_mad_u32_u24 v142, v142, s72, v143
	v_and_b32_e32 v144, 24, v144
	v_and_b32_e32 v132, 0xc0, v132
	v_add3_u32 v132, v142, v132, v144
	v_cvt_pk_bf16_f32 v93, v94, v95
	v_cvt_pk_bf16_f32 v84, v84, v85
	v_cvt_pk_bf16_f32 v85, v86, v87
	v_add_u32_e32 v94, 0x6000, v132
	ds_write2_b64 v94, v[92:93], v[84:85] offset0:96 offset1:100
	v_cvt_pk_bf16_f32 v84, v104, v105
	v_cvt_pk_bf16_f32 v85, v106, v107
	v_cvt_pk_bf16_f32 v86, v96, v97
	v_cvt_pk_bf16_f32 v87, v98, v99
	v_cvt_pk_bf16_f32 v124, v124, v125
	v_cvt_pk_bf16_f32 v125, v126, v127
	v_cvt_pk_bf16_f32 v120, v120, v121
	v_cvt_pk_bf16_f32 v121, v122, v123
	v_cvt_pk_bf16_f32 v116, v116, v117
	v_cvt_pk_bf16_f32 v117, v118, v119
	v_cvt_pk_bf16_f32 v112, v112, v113
	v_cvt_pk_bf16_f32 v113, v114, v115
	v_add_u32_e32 v114, 0x2000, v132
	v_cvt_pk_bf16_f32 v108, v108, v109
	v_cvt_pk_bf16_f32 v109, v110, v111
	v_cvt_pk_bf16_f32 v100, v100, v101
	v_cvt_pk_bf16_f32 v101, v102, v103
	v_add_u32_e32 v102, 0x4000, v132
	ds_write2_b64 v132, v[84:85], v[86:87] offset0:32 offset1:36
	v_cvt_pk_bf16_f32 v84, v88, v89
	v_cvt_pk_bf16_f32 v85, v90, v91
	v_cvt_pk_bf16_f32 v80, v80, v81
	v_cvt_pk_bf16_f32 v81, v82, v83
	v_cvt_pk_bf16_f32 v76, v76, v77
	v_cvt_pk_bf16_f32 v77, v78, v79
	v_cvt_pk_bf16_f32 v72, v72, v73
	v_cvt_pk_bf16_f32 v73, v74, v75
	v_cvt_pk_bf16_f32 v68, v68, v69
	v_cvt_pk_bf16_f32 v69, v70, v71
	v_cvt_pk_bf16_f32 v64, v64, v65
	v_cvt_pk_bf16_f32 v65, v66, v67
	ds_write2_b64 v132, v[124:125], v[120:121] offset1:4
	ds_write2_b64 v114, v[116:117], v[112:113] offset0:32 offset1:36
	ds_write2_b64 v102, v[108:109], v[100:101] offset0:64 offset1:68
	ds_write2_b64 v114, v[84:85], v[80:81] offset0:64 offset1:68
	ds_write2_b64 v102, v[76:77], v[72:73] offset0:96 offset1:100
	ds_write2_b64 v94, v[68:69], v[64:65] offset0:128 offset1:132
	v_mov_b32_e32 v64, v150
	s_waitcnt lgkmcnt(0)
	s_barrier
	s_lshl_b64 s[46:47], s[46:47], 1
	v_bfe_u32 v65, v64, 5, 1
	v_ashrrev_i32_e32 v66, 2, v64
	v_and_or_b32 v65, v66, -16, v65
	v_lshlrev_b32_e32 v64, 4, v64
	s_add_u32 s46, s58, s46
	v_and_b32_e32 v132, 0x1f0, v64
	v_mul_lo_u32 v64, v65, s72
	s_addc_u32 s47, s59, s47
	v_add3_u32 v78, s69, v64, v132
	v_add_u32_e32 v68, s44, v65
	v_mov_b64_e32 v[72:73], s[46:47]
	ds_read_b128 v[64:67], v78
	v_mad_i64_i32 v[68:69], s[44:45], v68, s73, v[72:73]
	v_lshl_add_u64 v[74:75], v[68:69], 0, v[132:133]
	ds_read_b128 v[68:71], v78 offset:1056
	s_waitcnt lgkmcnt(0)
	global_store_dwordx4 v[74:75], v[64:67], off nt
	v_cvt_pk_bf16_f32 v60, v60, v61
	v_cvt_pk_bf16_f32 v61, v62, v63
	v_add_co_u32_e32 v64, vcc, s74, v74
	v_cvt_pk_bf16_f32 v56, v56, v57
	s_nop 0
	v_addc_co_u32_e32 v65, vcc, 0, v75, vcc
	global_store_dwordx4 v[64:65], v[68:71], off offset:1024 nt
	ds_read_b128 v[64:67], v78 offset:2112
	ds_read_b128 v[68:71], v78 offset:3168
	v_add_co_u32_e32 v76, vcc, s71, v74
	v_cvt_pk_bf16_f32 v57, v58, v59
	s_nop 0
	v_addc_co_u32_e32 v77, vcc, 0, v75, vcc
	s_waitcnt lgkmcnt(0)
	global_store_dwordx4 v[76:77], v[64:67], off offset:2048 nt
	v_cvt_pk_bf16_f32 v52, v52, v53
	v_cvt_pk_bf16_f32 v53, v54, v55
	v_add_co_u32_e32 v64, vcc, s75, v74
	v_cvt_pk_bf16_f32 v48, v48, v49
	s_nop 0
	v_addc_co_u32_e32 v65, vcc, 0, v75, vcc
	global_store_dwordx4 v[64:65], v[68:71], off offset:3072 nt
	ds_read_b128 v[64:67], v78 offset:4224
	ds_read_b128 v[68:71], v78 offset:5280
	v_add_co_u32_e32 v76, vcc, s76, v74
	v_cvt_pk_bf16_f32 v49, v50, v51
	s_nop 0
	v_addc_co_u32_e32 v77, vcc, 0, v75, vcc
	s_waitcnt lgkmcnt(0)
	global_store_dwordx4 v[76:77], v[64:67], off nt
	v_cvt_pk_bf16_f32 v44, v44, v45
	v_cvt_pk_bf16_f32 v45, v46, v47
	v_add_co_u32_e32 v64, vcc, s77, v74
	v_cvt_pk_bf16_f32 v40, v40, v41
	s_nop 0
	v_addc_co_u32_e32 v65, vcc, 0, v75, vcc
	global_store_dwordx4 v[64:65], v[68:71], off offset:1024 nt
	ds_read_b128 v[64:67], v78 offset:6336
	ds_read_b128 v[68:71], v78 offset:7392
	v_add_co_u32_e32 v76, vcc, s78, v74
	v_cvt_pk_bf16_f32 v41, v42, v43
	s_nop 0
	v_addc_co_u32_e32 v77, vcc, 0, v75, vcc
	s_waitcnt lgkmcnt(0)
	global_store_dwordx4 v[76:77], v[64:67], off offset:2048 nt
	v_cvt_pk_bf16_f32 v36, v36, v37
	v_cvt_pk_bf16_f32 v37, v38, v39
	v_add_co_u32_e32 v64, vcc, s79, v74
	v_cvt_pk_bf16_f32 v32, v32, v33
	s_nop 0
	v_addc_co_u32_e32 v65, vcc, 0, v75, vcc
	global_store_dwordx4 v[64:65], v[68:71], off offset:3072 nt
	v_mov_b32_e32 v64, v150
	s_waitcnt lgkmcnt(0)
	s_barrier
; #define WAIT_L(n) asm volatile("s_waitcnt lgkmcnt(" #n ")" ::: "memory")
; #define BAR __builtin_amdgcn_s_barrier()
; template <int MODE, int N>
; __device__ __forceinline__ void gemm_phase(const bf16_t* __restrict__ A, const bf16_t* __restrict__ Bt,
;                            bf16_t* __restrict__ Cb, float* __restrict__ Cf, const float* __restrict__ resid,
;                            float alpha) {
;     ...
;         {
;           int el0 = gtid;
;           asm volatile("" : "+v"(el0));
;           char* lb = cst + (((el0 >> 8) & 1) * 64 + (el0 & 15)) * CROW + (((el0 >> 6) & 3) * 32 + ((el0 >> 4) & 3) * 4) * 2;
;           for (int bj = 0; bj < 2; ++bj)
;             for (int m = 0; m < 4; ++m)
;               for (int n = 0; n < 2; ++n) {
;                 f32x4 v = acc[ai][bj][m][n];
;                 uint2 o;
;                 o.x = pack2(v[0], v[1]);
;                 o.y = pack2(v[2], v[3]);
;                 *(uint2*)(lb + m * 16 * CROW + bj * HALF * 2 + n * 32) = o;
;               }
;         }
;         WAIT_L(0);
;         BAR;
;         asm volatile("" ::: "memory");
;         {
;           int el = gtid;
;           asm volatile("" : "+v"(el));
;           const int rsub = (el >> 5) & 1, cch = el & 31, rl0 = (el >> 6) * 16 + rsub;
;           bf16_t* cptr = Cb + (size_t)(brow + ai * HALF + rl0) * N + bcol + cch * 8;
;           const char* lptr = cst + rl0 * CROW + cch * 16;
; #pragma unroll
;           for (int i = 0; i < 8; ++i) {
;             typedef unsigned u32x4 __attribute__((ext_vector_type(4)));
;             u32x4 v = *(const u32x4*)(lptr + i * 2 * CROW);
;             __builtin_nontemporal_store(v, (u32x4*)cptr);
;             cptr += 2 * N;
;           }
;         }
;     ...
;     asm volatile("s_waitcnt vmcnt(0)" ::: "memory");
;     brow = nbrow;
;     bcol = nbcol;
	v_cvt_pk_bf16_f32 v33, v34, v35
	v_lshrrev_b32_e32 v65, 2, v64
	v_and_b32_e32 v66, 15, v64
	v_and_or_b32 v65, v65, 64, v66
	v_lshrrev_b32_e32 v66, 1, v64
	v_mad_u32_u24 v65, v65, s72, v143
	v_and_b32_e32 v66, 24, v66
	v_and_b32_e32 v64, 0xc0, v64
	v_add3_u32 v64, v65, v64, v66
	v_add_u32_e32 v50, 0x2000, v64
	v_add_u32_e32 v42, 0x4000, v64
	v_add_u32_e32 v34, 0x6000, v64
	v_cvt_pk_bf16_f32 v28, v28, v29
	v_cvt_pk_bf16_f32 v29, v30, v31
	v_cvt_pk_bf16_f32 v24, v24, v25
	v_cvt_pk_bf16_f32 v25, v26, v27
	v_cvt_pk_bf16_f32 v20, v20, v21
	v_cvt_pk_bf16_f32 v21, v22, v23
	v_cvt_pk_bf16_f32 v16, v16, v17
	v_cvt_pk_bf16_f32 v17, v18, v19
	v_cvt_pk_bf16_f32 v12, v12, v13
	v_cvt_pk_bf16_f32 v13, v14, v15
	v_cvt_pk_bf16_f32 v8, v8, v9
	v_cvt_pk_bf16_f32 v9, v10, v11
	v_cvt_pk_bf16_f32 v4, v4, v5
	v_cvt_pk_bf16_f32 v5, v6, v7
	v_cvt_pk_bf16_f32 v0, v0, v1
	v_cvt_pk_bf16_f32 v1, v2, v3
	ds_write2_b64 v64, v[60:61], v[56:57] offset1:4
	ds_write2_b64 v50, v[52:53], v[48:49] offset0:32 offset1:36
	ds_write2_b64 v42, v[44:45], v[40:41] offset0:64 offset1:68
	ds_write2_b64 v34, v[36:37], v[32:33] offset0:96 offset1:100
	ds_write2_b64 v64, v[28:29], v[24:25] offset0:32 offset1:36
	ds_write2_b64 v50, v[20:21], v[16:17] offset0:64 offset1:68
	ds_write2_b64 v42, v[12:13], v[8:9] offset0:96 offset1:100
	ds_write2_b64 v34, v[4:5], v[0:1] offset0:128 offset1:132
	v_mov_b32_e32 v0, v150
	s_waitcnt lgkmcnt(0)
	s_barrier
	s_mov_b32 s46, s54
	v_bfe_u32 v1, v0, 5, 1
	v_ashrrev_i32_e32 v2, 2, v0
	v_and_or_b32 v1, v2, -16, v1
	v_lshlrev_b32_e32 v0, 4, v0
	v_and_b32_e32 v132, 0x1f0, v0
	v_mul_lo_u32 v0, v1, s72
	v_add3_u32 v12, s69, v0, v132
	v_add_u32_e32 v4, s48, v1
	ds_read_b128 v[0:3], v12
	v_mad_i64_i32 v[4:5], s[44:45], v4, s73, v[72:73]
	v_lshl_add_u64 v[8:9], v[4:5], 0, v[132:133]
	ds_read_b128 v[4:7], v12 offset:1056
	s_waitcnt lgkmcnt(0)
	global_store_dwordx4 v[8:9], v[0:3], off nt
	s_mov_b32 s44, s52
	s_nop 0
	v_add_co_u32_e32 v0, vcc, s74, v8
	s_nop 1
	v_addc_co_u32_e32 v1, vcc, 0, v9, vcc
	global_store_dwordx4 v[0:1], v[4:7], off offset:1024 nt
	ds_read_b128 v[0:3], v12 offset:2112
	ds_read_b128 v[4:7], v12 offset:3168
	v_add_co_u32_e32 v10, vcc, s71, v8
	s_nop 1
	v_addc_co_u32_e32 v11, vcc, 0, v9, vcc
	s_waitcnt lgkmcnt(0)
	global_store_dwordx4 v[10:11], v[0:3], off offset:2048 nt
	s_nop 1
	v_add_co_u32_e32 v0, vcc, s75, v8
	s_nop 1
	v_addc_co_u32_e32 v1, vcc, 0, v9, vcc
	global_store_dwordx4 v[0:1], v[4:7], off offset:3072 nt
	ds_read_b128 v[0:3], v12 offset:4224
	ds_read_b128 v[4:7], v12 offset:5280
	v_add_co_u32_e32 v10, vcc, s76, v8
	s_nop 1
	v_addc_co_u32_e32 v11, vcc, 0, v9, vcc
	s_waitcnt lgkmcnt(0)
	global_store_dwordx4 v[10:11], v[0:3], off nt
	s_nop 1
	v_add_co_u32_e32 v0, vcc, s77, v8
	s_nop 1
	v_addc_co_u32_e32 v1, vcc, 0, v9, vcc
	global_store_dwordx4 v[0:1], v[4:7], off offset:1024 nt
	ds_read_b128 v[0:3], v12 offset:6336
	ds_read_b128 v[4:7], v12 offset:7392
	v_add_co_u32_e32 v10, vcc, 0x5b000, v8
	s_nop 1
	v_addc_co_u32_e32 v11, vcc, 0, v9, vcc
	s_waitcnt lgkmcnt(0)
	global_store_dwordx4 v[10:11], v[0:3], off offset:2048 nt
	s_nop 1
	v_add_co_u32_e32 v0, vcc, 0x6a000, v8
	s_nop 1
	v_addc_co_u32_e32 v1, vcc, 0, v9, vcc
	global_store_dwordx4 v[0:1], v[4:7], off offset:3072 nt
	s_waitcnt lgkmcnt(0)
	s_barrier
	s_waitcnt vmcnt(0)
	s_andn2_b64 vcc, exec, s[50:51]
	s_cbranch_vccz .LBB0_493

; #define WAIT_V(n) asm volatile("s_waitcnt vmcnt(" #n ")" ::: "memory")
; #define BAR __builtin_amdgcn_s_barrier()
; template <int MODE, int N>
; __device__ __forceinline__ void gemm_phase(const bf16_t* __restrict__ A, const bf16_t* __restrict__ Bt,
;                            bf16_t* __restrict__ Cb, float* __restrict__ Cf, const float* __restrict__ resid,
;                            float alpha) {
;     ...
;   for (int tile = blockIdx.x; tile < nwg; tile += gridDim.x) {
;     f32x4 acc[2][2][4][2] = {};
;     bf16x8 At[4][2], B0[2][2], B1[2][2];
;     if (wr == 1) BAR;
;     WAIT_V(4);
;     BAR;
;     STAGE(SB(1, 0), Bt, bcol, 1);
;     STAGE(SA(1, 0), A, brow, 1);
;     STAGE(SB(1, 1), Bt, bcol + HALF, 1);
;     WAIT_V(6);
;     BAR;
.LBB0_487:
	s_ashr_i32 s47, s46, 31
	s_lshl_b64 s[48:49], s[46:47], 13
	s_add_u32 s54, s56, s48
	s_addc_u32 s55, s57, s49
	v_lshl_add_u64 v[0:1], s[54:55], 0, v[134:135]
	s_add_i32 s50, s61, 0x18000
	s_ashr_i32 s45, s44, 31
	v_lshl_add_u64 v[0:1], v[0:1], 0, s[16:17]
	s_mov_b32 m0, s50
	s_add_i32 s51, s61, 0x1a000
	s_lshl_b64 s[82:83], s[44:45], 13
	s_waitcnt vmcnt(4)
	s_barrier
	global_load_lds_dwordx4 v[0:1], off
	v_lshl_add_u64 v[0:1], s[54:55], 0, v[136:137]
	s_add_u32 s52, s8, s82
	v_lshl_add_u64 v[0:1], v[0:1], 0, s[16:17]
	s_mov_b32 m0, s51
	s_addc_u32 s53, s9, s83
	global_load_lds_dwordx4 v[0:1], off
	v_lshl_add_u64 v[0:1], s[52:53], 0, v[134:135]
	s_add_i32 s45, s61, 0x10000
	v_lshl_add_u64 v[0:1], v[0:1], 0, s[16:17]
	s_mov_b32 m0, s45
	v_lshl_add_u64 v[142:143], v[138:139], 0, s[82:83]
	global_load_lds_dwordx4 v[0:1], off
	v_lshl_add_u64 v[0:1], s[52:53], 0, v[136:137]
	s_add_i32 s52, s61, 0x12000
	s_add_u32 s54, s54, 0x100000
	v_lshl_add_u64 v[0:1], v[0:1], 0, s[16:17]
	s_mov_b32 m0, s52
	s_addc_u32 s55, s55, 0
	global_load_lds_dwordx4 v[0:1], off
	v_lshl_add_u64 v[0:1], s[54:55], 0, v[134:135]
	s_add_i32 s53, s61, 0x1c000
	v_lshl_add_u64 v[0:1], v[0:1], 0, s[16:17]
	s_mov_b32 m0, s53
	v_lshl_add_u64 v[144:145], v[140:141], 0, s[82:83]
	global_load_lds_dwordx4 v[0:1], off
	v_lshl_add_u64 v[0:1], s[54:55], 0, v[136:137]
	s_add_i32 s54, s61, 0x1e000
	v_lshl_add_u64 v[0:1], v[0:1], 0, s[16:17]
	s_mov_b32 m0, s54
	v_lshl_add_u64 v[146:147], v[138:139], 0, s[48:49]
	global_load_lds_dwordx4 v[0:1], off
	s_waitcnt vmcnt(6)
	v_mov_b32_e32 v0, 0
	v_lshl_add_u64 v[148:149], v[140:141], 0, s[48:49]
	s_mov_b32 s55, -2
	s_mov_b64 s[48:49], s[10:11]
	v_mov_b32_e32 v1, v0
	v_mov_b32_e32 v2, v0
	v_mov_b32_e32 v3, v0
	v_mov_b32_e32 v4, v0
	v_mov_b32_e32 v5, v0
	v_mov_b32_e32 v6, v0
	v_mov_b32_e32 v7, v0
	v_mov_b32_e32 v8, v0
	v_mov_b32_e32 v9, v0
	v_mov_b32_e32 v10, v0
	v_mov_b32_e32 v11, v0
	v_mov_b32_e32 v12, v0
	v_mov_b32_e32 v13, v0
	v_mov_b32_e32 v14, v0
	v_mov_b32_e32 v15, v0
	v_mov_b32_e32 v16, v0
	v_mov_b32_e32 v17, v0
	v_mov_b32_e32 v18, v0
	v_mov_b32_e32 v19, v0
	v_mov_b32_e32 v20, v0
	v_mov_b32_e32 v21, v0
	v_mov_b32_e32 v22, v0
	v_mov_b32_e32 v23, v0
	v_mov_b32_e32 v24, v0
	v_mov_b32_e32 v25, v0
	v_mov_b32_e32 v26, v0
	v_mov_b32_e32 v27, v0
	v_mov_b32_e32 v28, v0
	v_mov_b32_e32 v29, v0
	v_mov_b32_e32 v30, v0
	v_mov_b32_e32 v31, v0
	v_mov_b32_e32 v32, v0
	v_mov_b32_e32 v33, v0
	v_mov_b32_e32 v34, v0
	v_mov_b32_e32 v35, v0
	v_mov_b32_e32 v36, v0
	v_mov_b32_e32 v37, v0
	v_mov_b32_e32 v38, v0
	v_mov_b32_e32 v39, v0
	v_mov_b32_e32 v40, v0
	v_mov_b32_e32 v41, v0
	v_mov_b32_e32 v42, v0
	v_mov_b32_e32 v43, v0
	v_mov_b32_e32 v44, v0
	v_mov_b32_e32 v45, v0
	v_mov_b32_e32 v46, v0
	v_mov_b32_e32 v47, v0
	v_mov_b32_e32 v48, v0
	v_mov_b32_e32 v49, v0
	v_mov_b32_e32 v50, v0
	v_mov_b32_e32 v51, v0
	v_mov_b32_e32 v52, v0
	v_mov_b32_e32 v53, v0
	v_mov_b32_e32 v54, v0
	v_mov_b32_e32 v55, v0
	v_mov_b32_e32 v56, v0
	v_mov_b32_e32 v57, v0
	v_mov_b32_e32 v58, v0
	v_mov_b32_e32 v59, v0
	v_mov_b32_e32 v60, v0
	v_mov_b32_e32 v61, v0
	v_mov_b32_e32 v62, v0
	v_mov_b32_e32 v63, v0
	v_mov_b32_e32 v64, v0
	v_mov_b32_e32 v65, v0
	v_mov_b32_e32 v66, v0
	v_mov_b32_e32 v67, v0
	v_mov_b32_e32 v68, v0
	v_mov_b32_e32 v69, v0
	v_mov_b32_e32 v70, v0
	v_mov_b32_e32 v71, v0
	v_mov_b32_e32 v72, v0
	v_mov_b32_e32 v73, v0
	v_mov_b32_e32 v74, v0
	v_mov_b32_e32 v75, v0
	v_mov_b32_e32 v76, v0
	v_mov_b32_e32 v77, v0
	v_mov_b32_e32 v78, v0
	v_mov_b32_e32 v79, v0
	v_mov_b32_e32 v80, v0
	v_mov_b32_e32 v81, v0
	v_mov_b32_e32 v82, v0
	v_mov_b32_e32 v83, v0
	v_mov_b32_e32 v84, v0
	v_mov_b32_e32 v85, v0
	v_mov_b32_e32 v86, v0
	v_mov_b32_e32 v87, v0
	v_mov_b32_e32 v88, v0
	v_mov_b32_e32 v89, v0
	v_mov_b32_e32 v90, v0
	v_mov_b32_e32 v91, v0
	v_mov_b32_e32 v92, v0
	v_mov_b32_e32 v93, v0
	v_mov_b32_e32 v94, v0
	v_mov_b32_e32 v95, v0
	v_mov_b32_e32 v96, v0
	v_mov_b32_e32 v97, v0
	v_mov_b32_e32 v98, v0
	v_mov_b32_e32 v99, v0
	v_mov_b32_e32 v100, v0
	v_mov_b32_e32 v101, v0
	v_mov_b32_e32 v102, v0
	v_mov_b32_e32 v103, v0
	v_mov_b32_e32 v104, v0
	v_mov_b32_e32 v105, v0
	v_mov_b32_e32 v106, v0
	v_mov_b32_e32 v107, v0
	v_mov_b32_e32 v108, v0
	v_mov_b32_e32 v109, v0
	v_mov_b32_e32 v110, v0
	v_mov_b32_e32 v111, v0
	v_mov_b32_e32 v112, v0
	v_mov_b32_e32 v113, v0
	v_mov_b32_e32 v114, v0
	v_mov_b32_e32 v115, v0
	v_mov_b32_e32 v116, v0
	v_mov_b32_e32 v117, v0
	v_mov_b32_e32 v118, v0
	v_mov_b32_e32 v119, v0
	v_mov_b32_e32 v120, v0
	v_mov_b32_e32 v121, v0
	v_mov_b32_e32 v122, v0
	v_mov_b32_e32 v123, v0
	v_mov_b32_e32 v124, v0
	v_mov_b32_e32 v125, v0
	v_mov_b32_e32 v126, v0
	v_mov_b32_e32 v127, v0
	s_barrier

; __device__ __forceinline__ void attn_phase(const bf16_t* __restrict__ proj, const bf16_t* __restrict__ KC,
;                            const bf16_t* __restrict__ VCT, const bf16_t* __restrict__ VT,
;                            bf16_t* __restrict__ mixed) {
;     ...
;       int nval = ((tk + 1) >> 4) - 1;
;       if (nval < 0) nval = 0;
;     ...
;       float mx = -1e30f;
; #pragma unroll
;       for (int mt = 0; mt < 16; ++mt)
; #pragma unroll
;         for (int jj = 0; jj < 4; ++jj) {
;           int n = mt * 16 + quad * 4 + jj;
;           float x = (n < nval) ? sc[mt][jj] * SCL : -1e30f;
;           sc[mt][jj] = x;
;           mx = fmaxf(mx, x);
;         }
.LBB0_603:
	v_ashrrev_i32_e32 v44, 4, v105
	v_max_i32_e32 v44, 1, v44
	v_add_u32_e32 v59, -1, v44
	s_nop 4
	v_pk_mul_f32 v[44:45], v[102:103], s[44:45] op_sel_hi:[1,0]
	v_cmp_lt_u32_e32 vcc, v179, v59
	v_pk_mul_f32 v[46:47], v[98:99], s[44:45] op_sel_hi:[1,0]
	v_pk_mul_f32 v[42:43], v[42:43], s[44:45] op_sel_hi:[1,0]
	v_cndmask_b32_e32 v102, v214, v45, vcc
	v_cmp_lt_u32_e32 vcc, v192, v59
	v_pk_mul_f32 v[40:41], v[40:41], s[44:45] op_sel_hi:[1,0]
	v_pk_mul_f32 v[38:39], v[38:39], s[44:45] op_sel_hi:[1,0]
	v_cndmask_b32_e32 v103, v214, v44, vcc
	v_pk_mul_f32 v[44:45], v[100:101], s[44:45] op_sel_hi:[1,0]
	v_cmp_lt_u32_e32 vcc, v177, v59
	v_pk_mul_f32 v[36:37], v[36:37], s[44:45] op_sel_hi:[1,0]
	v_pk_mul_f32 v[34:35], v[34:35], s[44:45] op_sel_hi:[1,0]
	v_cndmask_b32_e32 v100, v214, v45, vcc
	v_cmp_lt_u32_e32 vcc, v178, v59
	v_pk_mul_f32 v[32:33], v[32:33], s[44:45] op_sel_hi:[1,0]
	v_pk_mul_f32 v[30:31], v[30:31], s[44:45] op_sel_hi:[1,0]
	v_cndmask_b32_e32 v101, v214, v44, vcc
	v_cmp_lt_u32_e32 vcc, v175, v59
	v_pk_mul_f32 v[28:29], v[28:29], s[44:45] op_sel_hi:[1,0]
	v_pk_mul_f32 v[26:27], v[26:27], s[44:45] op_sel_hi:[1,0]
	v_cndmask_b32_e32 v44, v214, v47, vcc
	v_cmp_lt_u32_e32 vcc, v176, v59
	v_pk_mul_f32 v[24:25], v[24:25], s[44:45] op_sel_hi:[1,0]
	s_nop 0
	v_cndmask_b32_e32 v98, v214, v46, vcc
	v_pk_mul_f32 v[46:47], v[96:97], s[44:45] op_sel_hi:[1,0]
	v_cmp_lt_u32_e32 vcc, v173, v59
	s_nop 1
	v_cndmask_b32_e32 v45, v214, v47, vcc
	v_cmp_lt_u32_e32 vcc, v174, v59
	s_nop 1
	v_cndmask_b32_e32 v96, v214, v46, vcc
	v_pk_mul_f32 v[46:47], v[94:95], s[44:45] op_sel_hi:[1,0]
	v_cmp_lt_u32_e32 vcc, v171, v59
	s_nop 1
	v_cndmask_b32_e32 v52, v214, v47, vcc
	v_cmp_lt_u32_e32 vcc, v172, v59
	s_nop 1
	v_cndmask_b32_e32 v94, v214, v46, vcc
	v_pk_mul_f32 v[46:47], v[92:93], s[44:45] op_sel_hi:[1,0]
	v_cmp_lt_u32_e32 vcc, v169, v59
	s_nop 1
	v_cndmask_b32_e32 v53, v214, v47, vcc
	v_cmp_lt_u32_e32 vcc, v170, v59
	s_nop 1
	v_cndmask_b32_e32 v92, v214, v46, vcc
	v_pk_mul_f32 v[46:47], v[66:67], s[44:45] op_sel_hi:[1,0]
	v_cmp_lt_u32_e32 vcc, v167, v59
	s_nop 1
	v_cndmask_b32_e32 v56, v214, v47, vcc
	v_cmp_lt_u32_e32 vcc, v168, v59
	s_nop 1
	v_cndmask_b32_e32 v93, v214, v46, vcc
	v_pk_mul_f32 v[46:47], v[64:65], s[44:45] op_sel_hi:[1,0]
	v_cmp_lt_u32_e32 vcc, v165, v59
	s_nop 1
	v_cndmask_b32_e32 v54, v214, v47, vcc
	v_cmp_lt_u32_e32 vcc, v166, v59
	s_nop 1
	v_cndmask_b32_e32 v57, v214, v46, vcc
	v_pk_mul_f32 v[46:47], v[90:91], s[44:45] op_sel_hi:[1,0]
	v_cmp_lt_u32_e32 vcc, v163, v59
	s_nop 1
	v_cndmask_b32_e32 v55, v214, v47, vcc
	v_cmp_lt_u32_e32 vcc, v164, v59
	s_nop 1
	v_cndmask_b32_e32 v60, v214, v46, vcc
	v_pk_mul_f32 v[46:47], v[88:89], s[44:45] op_sel_hi:[1,0]
	v_cmp_lt_u32_e32 vcc, v161, v59
	s_nop 1
	v_cndmask_b32_e32 v58, v214, v47, vcc
	v_cmp_lt_u32_e32 vcc, v162, v59
	s_nop 1
	v_cndmask_b32_e32 v61, v214, v46, vcc
	v_pk_mul_f32 v[46:47], v[86:87], s[44:45] op_sel_hi:[1,0]
	v_cmp_lt_u32_e32 vcc, v159, v59
	s_nop 1
	v_cndmask_b32_e32 v90, v214, v47, vcc
	v_cmp_lt_u32_e32 vcc, v160, v59
	s_nop 1
	v_cndmask_b32_e32 v91, v214, v46, vcc
	v_pk_mul_f32 v[46:47], v[84:85], s[44:45] op_sel_hi:[1,0]
	v_cmp_lt_u32_e32 vcc, v157, v59
	s_nop 1
	v_cndmask_b32_e32 v62, v214, v47, vcc
	v_cmp_lt_u32_e32 vcc, v158, v59
	s_nop 1
	v_cndmask_b32_e32 v95, v214, v46, vcc
	v_pk_mul_f32 v[46:47], v[82:83], s[44:45] op_sel_hi:[1,0]
	v_cmp_lt_u32_e32 vcc, v155, v59
	s_nop 1
	v_cndmask_b32_e32 v63, v214, v47, vcc
	v_cmp_lt_u32_e32 vcc, v156, v59
	s_nop 1
	v_cndmask_b32_e32 v97, v214, v46, vcc
	v_pk_mul_f32 v[46:47], v[80:81], s[44:45] op_sel_hi:[1,0]
	v_cmp_lt_u32_e32 vcc, v153, v59
	s_nop 1
	v_cndmask_b32_e32 v99, v214, v47, vcc
	v_cmp_lt_u32_e32 vcc, v154, v59
	s_nop 1
	v_cndmask_b32_e32 v105, v214, v46, vcc
	v_pk_mul_f32 v[46:47], v[78:79], s[44:45] op_sel_hi:[1,0]
	v_cmp_lt_u32_e32 vcc, v151, v59
	s_nop 1
	v_cndmask_b32_e32 v66, v214, v47, vcc
	v_cmp_lt_u32_e32 vcc, v152, v59
	s_nop 1
	v_cndmask_b32_e32 v190, v214, v46, vcc
	v_pk_mul_f32 v[46:47], v[76:77], s[44:45] op_sel_hi:[1,0]
	v_cmp_lt_u32_e32 vcc, v149, v59
	s_nop 1
	v_cndmask_b32_e32 v64, v214, v47, vcc
	v_cmp_lt_u32_e32 vcc, v150, v59
	s_nop 1
	v_cndmask_b32_e32 v67, v214, v46, vcc
	v_pk_mul_f32 v[46:47], v[74:75], s[44:45] op_sel_hi:[1,0]
	v_cmp_lt_u32_e32 vcc, v147, v59
	s_nop 1
	v_cndmask_b32_e32 v65, v214, v47, vcc
	v_cmp_lt_u32_e32 vcc, v148, v59
	s_nop 1
	v_cndmask_b32_e32 v74, v214, v46, vcc
	v_pk_mul_f32 v[46:47], v[72:73], s[44:45] op_sel_hi:[1,0]
	v_cmp_lt_u32_e32 vcc, v145, v59
	s_nop 1
	v_cndmask_b32_e32 v72, v214, v47, vcc
	v_cmp_lt_u32_e32 vcc, v146, v59
	s_nop 1
	v_cndmask_b32_e32 v75, v214, v46, vcc
	v_pk_mul_f32 v[46:47], v[70:71], s[44:45] op_sel_hi:[1,0]
	v_cmp_lt_u32_e32 vcc, v143, v59
	s_nop 1
	v_cndmask_b32_e32 v70, v214, v47, vcc
	v_cmp_lt_u32_e32 vcc, v144, v59
	s_nop 1
	v_cndmask_b32_e32 v71, v214, v46, vcc
	v_pk_mul_f32 v[46:47], v[68:69], s[44:45] op_sel_hi:[1,0]
	v_cmp_lt_u32_e32 vcc, v141, v59
	s_nop 1
	v_cndmask_b32_e32 v68, v214, v47, vcc
	v_cmp_lt_u32_e32 vcc, v142, v59
	s_nop 1
	v_cndmask_b32_e32 v69, v214, v46, vcc
	v_pk_mul_f32 v[46:47], v[50:51], s[44:45] op_sel_hi:[1,0]
	v_cmp_lt_u32_e32 vcc, v139, v59
	s_nop 1
	v_cndmask_b32_e32 v50, v214, v47, vcc
	v_cmp_lt_u32_e32 vcc, v140, v59
	s_nop 1
	v_cndmask_b32_e32 v51, v214, v46, vcc
	v_pk_mul_f32 v[46:47], v[48:49], s[44:45] op_sel_hi:[1,0]
	v_cmp_lt_u32_e32 vcc, v137, v59
	s_nop 1
	v_cndmask_b32_e32 v73, v214, v47, vcc
	v_cmp_lt_u32_e32 vcc, v138, v59
	s_nop 1
	v_cndmask_b32_e32 v76, v214, v46, vcc
	v_cmp_lt_u32_e32 vcc, v135, v59
	s_nop 1
	v_cndmask_b32_e32 v77, v214, v43, vcc
	v_cmp_lt_u32_e32 vcc, v136, v59
; __device__ __forceinline__ void attn_phase(const bf16_t* __restrict__ proj, const bf16_t* __restrict__ KC,
;                            const bf16_t* __restrict__ VCT, const bf16_t* __restrict__ VT,
;                            bf16_t* __restrict__ mixed) {
;     ...
;       float mx = -1e30f;
; #pragma unroll
;       for (int mt = 0; mt < 16; ++mt)
; #pragma unroll
;         for (int jj = 0; jj < 4; ++jj) {
;           int n = mt * 16 + quad * 4 + jj;
;           float x = (n < nval) ? sc[mt][jj] * SCL : -1e30f;
;           sc[mt][jj] = x;
;           mx = fmaxf(mx, x);
;         }
;       mx = quad_max(mx);
;       float lsum = 0.f;
; #pragma unroll
;       for (int mt = 0; mt < 16; ++mt)
; #pragma unroll
;         for (int jj = 0; jj < 4; ++jj) {
;           float x = sc[mt][jj];
;           float p = (x > -1e29f) ? __builtin_amdgcn_exp2f(x - mx) : 0.f;
;           sc[mt][jj] = p;
;           lsum += p;
;         }
;       lsum = quad_sum(lsum);
	s_nop 1
	v_cndmask_b32_e32 v78, v214, v42, vcc
	v_cmp_lt_u32_e32 vcc, v133, v59
	s_nop 1
	v_cndmask_b32_e32 v79, v214, v41, vcc
	v_cmp_lt_u32_e32 vcc, v134, v59
	s_nop 1
	v_cndmask_b32_e32 v80, v214, v40, vcc
	v_cmp_lt_u32_e32 vcc, v131, v59
	s_nop 1
	v_cndmask_b32_e32 v48, v214, v39, vcc
	v_cmp_lt_u32_e32 vcc, v132, v59
	s_nop 1
	v_cndmask_b32_e32 v81, v214, v38, vcc
	v_cmp_lt_u32_e32 vcc, v129, v59
	s_nop 1
	v_cndmask_b32_e32 v46, v214, v37, vcc
	v_cmp_lt_u32_e32 vcc, v130, v59
	s_nop 1
	v_cndmask_b32_e32 v49, v214, v36, vcc
	v_cmp_lt_u32_e32 vcc, v127, v59
	s_nop 1
	v_cndmask_b32_e32 v42, v214, v35, vcc
	v_cmp_lt_u32_e32 vcc, v128, v59
	s_nop 1
	v_cndmask_b32_e32 v47, v214, v34, vcc
	v_cmp_lt_u32_e32 vcc, v125, v59
	s_nop 1
	v_cndmask_b32_e32 v40, v214, v33, vcc
	v_cmp_lt_u32_e32 vcc, v126, v59
	s_nop 1
	v_cndmask_b32_e32 v43, v214, v32, vcc
	v_cmp_lt_u32_e32 vcc, v123, v59
	s_nop 1
	v_cndmask_b32_e32 v31, v214, v31, vcc
	v_cmp_lt_u32_e32 vcc, v124, v59
	s_nop 1
	v_cndmask_b32_e32 v30, v214, v30, vcc
	v_cmp_lt_u32_e32 vcc, v121, v59
	s_nop 1
	v_cndmask_b32_e32 v29, v214, v29, vcc
	v_cmp_lt_u32_e32 vcc, v122, v59
	s_nop 1
	v_cndmask_b32_e32 v28, v214, v28, vcc
	v_cmp_lt_u32_e32 vcc, v111, v59
	s_nop 1
	v_cndmask_b32_e32 v27, v214, v27, vcc
	v_cmp_lt_u32_e32 vcc, v120, v59
	s_nop 1
	v_cndmask_b32_e32 v26, v214, v26, vcc
	v_cmp_lt_u32_e32 vcc, v107, v59
	s_nop 1
	v_cndmask_b32_e32 v25, v214, v25, vcc
	v_cmp_lt_u32_e32 vcc, v188, v59
	s_nop 1
	v_cndmask_b32_e32 v24, v214, v24, vcc
	v_max3_f32 v32, v24, s82, v25
	v_max3_f32 v32, v32, v26, v27
	v_max3_f32 v32, v32, v28, v29
	v_max3_f32 v32, v32, v30, v31
	v_max3_f32 v32, v32, v43, v40
	v_max3_f32 v32, v32, v47, v42
	v_max3_f32 v32, v32, v49, v46
	v_max3_f32 v32, v32, v81, v48
	v_max3_f32 v32, v32, v80, v79
	v_max3_f32 v32, v32, v78, v77
	v_max3_f32 v32, v32, v76, v73
	v_max3_f32 v32, v32, v51, v50
	v_max3_f32 v32, v32, v69, v68
	v_max3_f32 v32, v32, v71, v70
	v_max3_f32 v32, v32, v75, v72
	v_max3_f32 v32, v32, v74, v65
	v_max3_f32 v32, v32, v67, v64
	v_max3_f32 v32, v32, v190, v66
	v_max3_f32 v32, v32, v105, v99
	v_max3_f32 v32, v32, v97, v63
	v_max3_f32 v32, v32, v95, v62
	v_max3_f32 v32, v32, v91, v90
	v_max3_f32 v32, v32, v61, v58
	v_max3_f32 v32, v32, v60, v55
	v_max3_f32 v32, v32, v57, v54
	v_max3_f32 v32, v32, v93, v56
	v_max3_f32 v32, v32, v92, v53
	v_max3_f32 v32, v32, v94, v52
	v_max3_f32 v32, v32, v96, v45
	v_max3_f32 v32, v32, v98, v44
	v_max3_f32 v32, v32, v101, v100
	v_max3_f32 v32, v32, v103, v102
	v_mov_b32_e32 v33, v32
	s_nop 1
	v_permlane16_swap_b32_e32 v32, v33
	v_max_f32_e32 v33, v33, v33
	v_max_f32_e32 v32, v32, v32
	v_max_f32_e32 v32, v32, v33
	v_mov_b32_e32 v33, v32
	s_nop 1
	v_permlane32_swap_b32_e32 v32, v33
	v_max_f32_e32 v33, v33, v33
	v_max_f32_e32 v32, v32, v32
	v_max_f32_e32 v191, v32, v33
	v_sub_f32_e32 v32, v25, v191
	v_exp_f32_e32 v32, v32
	v_sub_f32_e32 v33, v24, v191
	v_exp_f32_e32 v33, v33
	v_cmp_lt_f32_e32 vcc, s83, v25
	v_sub_f32_e32 v25, v27, v191
	v_exp_f32_e32 v25, v25
	v_cndmask_b32_e32 v35, 0, v32, vcc
	v_cmp_lt_f32_e32 vcc, s83, v24
	v_sub_f32_e32 v32, v26, v191
	v_exp_f32_e32 v32, v32
	v_cndmask_b32_e32 v34, 0, v33, vcc
	v_cmp_lt_f32_e32 vcc, s83, v27
	v_add_f32_e32 v24, 0, v34
	v_add_f32_e32 v24, v35, v24
	v_cndmask_b32_e32 v33, 0, v25, vcc
	v_sub_f32_e32 v25, v29, v191
	v_cmp_lt_f32_e32 vcc, s83, v26
	v_exp_f32_e32 v25, v25
	v_sub_f32_e32 v26, v28, v191
	v_exp_f32_e32 v26, v26
	v_cndmask_b32_e32 v32, 0, v32, vcc
	v_cmp_lt_f32_e32 vcc, s83, v29
	v_add_f32_e32 v24, v32, v24
	v_add_f32_e32 v24, v33, v24
	v_cndmask_b32_e32 v37, 0, v25, vcc
	v_cmp_lt_f32_e32 vcc, s83, v28
	v_sub_f32_e32 v25, v31, v191
	v_exp_f32_e32 v25, v25
	v_cndmask_b32_e32 v36, 0, v26, vcc
	v_sub_f32_e32 v26, v30, v191
	v_exp_f32_e32 v26, v26
	v_cmp_lt_f32_e32 vcc, s83, v31
	v_add_f32_e32 v24, v36, v24
	v_add_f32_e32 v24, v37, v24
	v_cndmask_b32_e32 v39, 0, v25, vcc
	v_cmp_lt_f32_e32 vcc, s83, v30
	v_sub_f32_e32 v25, v40, v191
	v_exp_f32_e32 v25, v25
	v_cndmask_b32_e32 v38, 0, v26, vcc
	v_sub_f32_e32 v26, v43, v191
	v_exp_f32_e32 v26, v26
	v_cmp_lt_f32_e32 vcc, s83, v40
	v_add_f32_e32 v24, v38, v24
	v_add_f32_e32 v24, v39, v24
	v_cndmask_b32_e32 v41, 0, v25, vcc
	v_cmp_lt_f32_e32 vcc, s83, v43
	v_sub_f32_e32 v25, v42, v191
	v_exp_f32_e32 v25, v25
	v_cndmask_b32_e32 v40, 0, v26, vcc
	v_sub_f32_e32 v26, v47, v191
	v_exp_f32_e32 v26, v26
	v_cmp_lt_f32_e32 vcc, s83, v42
	v_add_f32_e32 v24, v40, v24
	v_add_f32_e32 v24, v41, v24
	v_cndmask_b32_e32 v43, 0, v25, vcc
	v_cmp_lt_f32_e32 vcc, s83, v47
	v_sub_f32_e32 v25, v46, v191
	v_exp_f32_e32 v25, v25
	v_cndmask_b32_e32 v42, 0, v26, vcc
	v_sub_f32_e32 v26, v49, v191
	v_exp_f32_e32 v26, v26
	v_cmp_lt_f32_e32 vcc, s83, v46
	v_add_f32_e32 v24, v42, v24
	v_add_f32_e32 v24, v43, v24
	v_cndmask_b32_e32 v47, 0, v25, vcc
	v_cmp_lt_f32_e32 vcc, s83, v49
	v_sub_f32_e32 v25, v48, v191
	v_exp_f32_e32 v25, v25
	v_cndmask_b32_e32 v46, 0, v26, vcc
	v_sub_f32_e32 v26, v81, v191
	v_exp_f32_e32 v26, v26
	v_cmp_lt_f32_e32 vcc, s83, v48
	v_add_f32_e32 v24, v46, v24
	v_add_f32_e32 v24, v47, v24
	v_cndmask_b32_e32 v49, 0, v25, vcc
	v_cmp_lt_f32_e32 vcc, s83, v81
	v_sub_f32_e32 v25, v79, v191
	v_exp_f32_e32 v25, v25
	v_cndmask_b32_e32 v48, 0, v26, vcc
	v_sub_f32_e32 v26, v80, v191
	v_exp_f32_e32 v26, v26
	v_cmp_lt_f32_e32 vcc, s83, v79
	v_add_f32_e32 v24, v48, v24
	v_add_f32_e32 v24, v49, v24
	v_cndmask_b32_e32 v85, 0, v25, vcc
	v_cmp_lt_f32_e32 vcc, s83, v80
	v_sub_f32_e32 v25, v77, v191
	v_exp_f32_e32 v25, v25
	v_cndmask_b32_e32 v84, 0, v26, vcc
	v_sub_f32_e32 v26, v78, v191
	v_exp_f32_e32 v26, v26
	v_cmp_lt_f32_e32 vcc, s83, v77
	v_add_f32_e32 v24, v84, v24
; __device__ __forceinline__ void attn_phase(const bf16_t* __restrict__ proj, const bf16_t* __restrict__ KC,
;                            const bf16_t* __restrict__ VCT, const bf16_t* __restrict__ VT,
;                            bf16_t* __restrict__ mixed) {
;     ...
;       float lsum = 0.f;
; #pragma unroll
;       for (int mt = 0; mt < 16; ++mt)
; #pragma unroll
;         for (int jj = 0; jj < 4; ++jj) {
;           float x = sc[mt][jj];
;           float p = (x > -1e29f) ? __builtin_amdgcn_exp2f(x - mx) : 0.f;
;           sc[mt][jj] = p;
;           lsum += p;
;         }
;       lsum = quad_sum(lsum);
	v_add_f32_e32 v24, v85, v24
	v_cndmask_b32_e32 v87, 0, v25, vcc
	v_cmp_lt_f32_e32 vcc, s83, v78
	v_sub_f32_e32 v25, v73, v191
	v_exp_f32_e32 v25, v25
	v_cndmask_b32_e32 v86, 0, v26, vcc
	v_sub_f32_e32 v26, v76, v191
	v_exp_f32_e32 v26, v26
	v_cmp_lt_f32_e32 vcc, s83, v73
	v_add_f32_e32 v24, v86, v24
	v_add_f32_e32 v24, v87, v24
	v_cndmask_b32_e32 v83, 0, v25, vcc
	v_cmp_lt_f32_e32 vcc, s83, v76
	v_sub_f32_e32 v25, v50, v191
	v_exp_f32_e32 v25, v25
	v_cndmask_b32_e32 v82, 0, v26, vcc
	v_sub_f32_e32 v26, v51, v191
	v_exp_f32_e32 v26, v26
	v_cmp_lt_f32_e32 vcc, s83, v50
	v_add_f32_e32 v24, v82, v24
	v_add_f32_e32 v24, v83, v24
	v_cndmask_b32_e32 v89, 0, v25, vcc
	v_cmp_lt_f32_e32 vcc, s83, v51
	v_sub_f32_e32 v25, v68, v191
	v_exp_f32_e32 v25, v25
	v_cndmask_b32_e32 v88, 0, v26, vcc
	v_sub_f32_e32 v26, v69, v191
	v_exp_f32_e32 v26, v26
	v_cmp_lt_f32_e32 vcc, s83, v68
	v_add_f32_e32 v24, v88, v24
	v_add_f32_e32 v24, v89, v24
	v_cndmask_b32_e32 v79, 0, v25, vcc
	v_cmp_lt_f32_e32 vcc, s83, v69
	v_sub_f32_e32 v25, v70, v191
	v_exp_f32_e32 v25, v25
	v_cndmask_b32_e32 v78, 0, v26, vcc
	v_sub_f32_e32 v26, v71, v191
	v_exp_f32_e32 v26, v26
	v_cmp_lt_f32_e32 vcc, s83, v70
	v_add_f32_e32 v24, v78, v24
	v_add_f32_e32 v24, v79, v24
	v_cndmask_b32_e32 v81, 0, v25, vcc
	v_cmp_lt_f32_e32 vcc, s83, v71
	v_sub_f32_e32 v25, v72, v191
	v_exp_f32_e32 v25, v25
	v_cndmask_b32_e32 v80, 0, v26, vcc
	v_sub_f32_e32 v26, v75, v191
	v_exp_f32_e32 v26, v26
	v_cmp_lt_f32_e32 vcc, s83, v72
	v_add_f32_e32 v24, v80, v24
	v_add_f32_e32 v24, v81, v24
	v_cndmask_b32_e32 v73, 0, v25, vcc
	v_cmp_lt_f32_e32 vcc, s83, v75
	v_sub_f32_e32 v25, v65, v191
	v_exp_f32_e32 v25, v25
	v_cndmask_b32_e32 v72, 0, v26, vcc
	v_sub_f32_e32 v26, v74, v191
	v_exp_f32_e32 v26, v26
	v_cmp_lt_f32_e32 vcc, s83, v65
	v_add_f32_e32 v24, v72, v24
	v_add_f32_e32 v24, v73, v24
	v_cndmask_b32_e32 v77, 0, v25, vcc
	v_cmp_lt_f32_e32 vcc, s83, v74
	v_sub_f32_e32 v25, v64, v191
	v_exp_f32_e32 v25, v25
	v_cndmask_b32_e32 v76, 0, v26, vcc
	v_sub_f32_e32 v26, v67, v191
	v_exp_f32_e32 v26, v26
	v_cmp_lt_f32_e32 vcc, s83, v64
	v_add_f32_e32 v24, v76, v24
	v_add_f32_e32 v24, v77, v24
	v_cndmask_b32_e32 v65, 0, v25, vcc
	v_cmp_lt_f32_e32 vcc, s83, v67
	v_sub_f32_e32 v25, v66, v191
	v_exp_f32_e32 v25, v25
	v_cndmask_b32_e32 v64, 0, v26, vcc
	v_sub_f32_e32 v26, v190, v191
	v_exp_f32_e32 v26, v26
	v_cmp_lt_f32_e32 vcc, s83, v66
	v_add_f32_e32 v24, v64, v24
	v_add_f32_e32 v24, v65, v24
	v_cndmask_b32_e32 v67, 0, v25, vcc
	v_cmp_lt_f32_e32 vcc, s83, v190
	v_sub_f32_e32 v25, v99, v191
	v_exp_f32_e32 v25, v25
	v_cndmask_b32_e32 v66, 0, v26, vcc
	v_sub_f32_e32 v26, v105, v191
	v_exp_f32_e32 v26, v26
	v_cmp_lt_f32_e32 vcc, s83, v99
	v_add_f32_e32 v24, v66, v24
	v_add_f32_e32 v24, v67, v24
	v_cndmask_b32_e32 v69, 0, v25, vcc
	v_cmp_lt_f32_e32 vcc, s83, v105
	v_sub_f32_e32 v25, v63, v191
	v_exp_f32_e32 v25, v25
	v_cndmask_b32_e32 v68, 0, v26, vcc
	v_sub_f32_e32 v26, v97, v191
	v_exp_f32_e32 v26, v26
	v_cmp_lt_f32_e32 vcc, s83, v63
	v_add_f32_e32 v24, v68, v24
	v_add_f32_e32 v24, v69, v24
	v_cndmask_b32_e32 v71, 0, v25, vcc
	v_cmp_lt_f32_e32 vcc, s83, v97
	v_sub_f32_e32 v25, v62, v191
	v_exp_f32_e32 v25, v25
	v_cndmask_b32_e32 v70, 0, v26, vcc
	v_sub_f32_e32 v26, v95, v191
	v_exp_f32_e32 v26, v26
	v_cmp_lt_f32_e32 vcc, s83, v62
	v_add_f32_e32 v24, v70, v24
	v_add_f32_e32 v24, v71, v24
	v_cndmask_b32_e32 v63, 0, v25, vcc
	v_cmp_lt_f32_e32 vcc, s83, v95
	v_sub_f32_e32 v25, v90, v191
	v_exp_f32_e32 v25, v25
	v_cndmask_b32_e32 v62, 0, v26, vcc
	v_sub_f32_e32 v26, v91, v191
	v_exp_f32_e32 v26, v26
	v_cmp_lt_f32_e32 vcc, s83, v90
	v_add_f32_e32 v24, v62, v24
	v_add_f32_e32 v24, v63, v24
	v_cndmask_b32_e32 v75, 0, v25, vcc
	v_cmp_lt_f32_e32 vcc, s83, v91
	v_sub_f32_e32 v25, v58, v191
	v_exp_f32_e32 v25, v25
	v_cndmask_b32_e32 v74, 0, v26, vcc
	v_sub_f32_e32 v26, v61, v191
	v_exp_f32_e32 v26, v26
	v_cmp_lt_f32_e32 vcc, s83, v58
	v_add_f32_e32 v24, v74, v24
	v_add_f32_e32 v24, v75, v24
	v_cndmask_b32_e32 v59, 0, v25, vcc
	v_cmp_lt_f32_e32 vcc, s83, v61
	v_sub_f32_e32 v25, v55, v191
	v_exp_f32_e32 v25, v25
	v_cndmask_b32_e32 v58, 0, v26, vcc
	v_sub_f32_e32 v26, v60, v191
	v_exp_f32_e32 v26, v26
	v_cmp_lt_f32_e32 vcc, s83, v55
	v_add_f32_e32 v24, v58, v24
	v_add_f32_e32 v24, v59, v24
	v_cndmask_b32_e32 v61, 0, v25, vcc
	v_cmp_lt_f32_e32 vcc, s83, v60
	v_sub_f32_e32 v25, v54, v191
	v_exp_f32_e32 v25, v25
	v_cndmask_b32_e32 v60, 0, v26, vcc
	v_sub_f32_e32 v26, v57, v191
	v_exp_f32_e32 v26, v26
	v_cmp_lt_f32_e32 vcc, s83, v54
	v_add_f32_e32 v24, v60, v24
	v_add_f32_e32 v24, v61, v24
	v_cndmask_b32_e32 v55, 0, v25, vcc
	v_cmp_lt_f32_e32 vcc, s83, v57
	v_sub_f32_e32 v25, v56, v191
	v_exp_f32_e32 v25, v25
	v_cndmask_b32_e32 v54, 0, v26, vcc
	v_sub_f32_e32 v26, v93, v191
	v_exp_f32_e32 v26, v26
	v_cmp_lt_f32_e32 vcc, s83, v56
	v_add_f32_e32 v24, v54, v24
	v_add_f32_e32 v24, v55, v24
	v_cndmask_b32_e32 v57, 0, v25, vcc
	v_cmp_lt_f32_e32 vcc, s83, v93
	v_sub_f32_e32 v25, v53, v191
	v_exp_f32_e32 v25, v25
	v_cndmask_b32_e32 v56, 0, v26, vcc
	v_sub_f32_e32 v26, v92, v191
	v_exp_f32_e32 v26, v26
	v_cmp_lt_f32_e32 vcc, s83, v53
	v_add_f32_e32 v24, v56, v24
	v_add_f32_e32 v24, v57, v24
	v_cndmask_b32_e32 v51, 0, v25, vcc
	v_cmp_lt_f32_e32 vcc, s83, v92
	v_sub_f32_e32 v25, v52, v191
	v_exp_f32_e32 v25, v25
	v_cndmask_b32_e32 v50, 0, v26, vcc
	v_sub_f32_e32 v26, v94, v191
	v_exp_f32_e32 v26, v26
	v_cmp_lt_f32_e32 vcc, s83, v52
	v_add_f32_e32 v24, v50, v24
	v_add_f32_e32 v24, v51, v24
	v_cndmask_b32_e32 v53, 0, v25, vcc
	v_cmp_lt_f32_e32 vcc, s83, v94
	v_sub_f32_e32 v25, v45, v191
	v_exp_f32_e32 v25, v25
	v_cndmask_b32_e32 v52, 0, v26, vcc
; __device__ __forceinline__ void attn_phase(const bf16_t* __restrict__ proj, const bf16_t* __restrict__ KC,
;                            const bf16_t* __restrict__ VCT, const bf16_t* __restrict__ VT,
;                            bf16_t* __restrict__ mixed) {
;     ...
;       lsum = quad_sum(lsum);
;       const float inv = lsum > 0.f ? 1.0f / lsum : 0.f;
;       float rot_prev = 0.f;
; #pragma unroll
;       for (int mt = 0; mt < 16; ++mt) {
;         sc[mt][0] *= inv; sc[mt][1] *= inv; sc[mt][2] *= inv; sc[mt][3] *= inv;
;         float own = (sc[mt][0] + sc[mt][1]) + (sc[mt][2] + sc[mt][3]);
;         float rot = __shfl(sc[mt][3], (lane + 48) & 63);
;         float prev = (quad == 0) ? rot_prev : rot;
;         rot_prev = rot;
;         float ps = own + prev;
;         ps += __shfl_xor(ps, 1);
;         ps += __shfl_xor(ps, 2);
;         if (r == 0) pslc[(w * 8 + qs * 4 + tl) * 64 + mt * 4 + quad] = ps;
;       }
	v_sub_f32_e32 v26, v96, v191
	v_exp_f32_e32 v26, v26
	v_cmp_lt_f32_e32 vcc, s83, v45
	v_add_f32_e32 v24, v52, v24
	v_add_f32_e32 v24, v53, v24
	v_cndmask_b32_e32 v31, 0, v25, vcc
	v_cmp_lt_f32_e32 vcc, s83, v96
	v_sub_f32_e32 v25, v44, v191
	v_exp_f32_e32 v25, v25
	v_cndmask_b32_e32 v30, 0, v26, vcc
	v_sub_f32_e32 v26, v98, v191
	v_exp_f32_e32 v26, v26
	v_cmp_lt_f32_e32 vcc, s83, v44
	v_add_f32_e32 v24, v30, v24
	v_add_f32_e32 v24, v31, v24
	v_cndmask_b32_e32 v45, 0, v25, vcc
	v_cmp_lt_f32_e32 vcc, s83, v98
	v_sub_f32_e32 v25, v101, v191
	v_exp_f32_e32 v27, v25
	v_cndmask_b32_e32 v44, 0, v26, vcc
	v_add_f32_e32 v24, v44, v24
	v_add_f32_e32 v26, v45, v24
	v_sub_f32_e32 v24, v100, v191
	v_exp_f32_e32 v24, v24
	v_cmp_lt_f32_e32 vcc, s83, v100
	s_nop 1
	v_cndmask_b32_e32 v25, 0, v24, vcc
	v_cmp_lt_f32_e32 vcc, s83, v101
	s_nop 1
	v_cndmask_b32_e32 v24, 0, v27, vcc
	v_add_f32_e32 v26, v24, v26
	v_add_f32_e32 v28, v25, v26
	v_sub_f32_e32 v26, v102, v191
	v_exp_f32_e32 v26, v26
	v_sub_f32_e32 v27, v103, v191
	v_exp_f32_e32 v29, v27
	v_cmp_lt_f32_e32 vcc, s83, v102
	s_nop 1
	v_cndmask_b32_e32 v27, 0, v26, vcc
	v_cmp_lt_f32_e32 vcc, s83, v103
	s_nop 1
	v_cndmask_b32_e32 v26, 0, v29, vcc
	v_add_f32_e32 v28, v26, v28
	v_add_f32_e32 v28, v27, v28
	v_mov_b32_e32 v29, v28
	s_nop 1
	v_permlane16_swap_b32_e32 v28, v29
	v_add_f32_e32 v28, v28, v29
	v_mov_b32_e32 v29, v28
	s_nop 1
	v_permlane32_swap_b32_e32 v28, v29
	v_add_f32_e32 v28, v28, v29
	v_div_scale_f32 v29, s[68:69], v28, v28, 1.0
	v_rcp_f32_e32 v90, v29
	s_nop 0
	v_fma_f32 v91, -v29, v90, 1.0
	v_fmac_f32_e32 v90, v91, v90
	v_div_scale_f32 v91, vcc, 1.0, v28, 1.0
	v_mul_f32_e32 v92, v91, v90
	v_fma_f32 v93, -v29, v92, v91
	v_fmac_f32_e32 v92, v93, v90
	v_fma_f32 v29, -v29, v92, v91
	v_div_fmas_f32 v29, v29, v90, v92
	v_div_fixup_f32 v29, v29, v28, 1.0
	v_cmp_lt_f32_e32 vcc, 0, v28
	v_or_b32_e32 v92, s9, v225
	v_lshlrev_b32_e32 v92, 8, v92
	v_cndmask_b32_e32 v28, 0, v29, vcc
	v_pk_mul_f32 v[32:33], v[28:29], v[32:33] op_sel_hi:[0,1]
	ds_bpermute_b32 v91, v219, v33
	v_pk_mul_f32 v[34:35], v[28:29], v[34:35] op_sel_hi:[0,1]
	v_add_f32_e32 v29, v32, v33
	v_add_f32_e32 v90, v34, v35
	v_add_f32_e32 v29, v90, v29
	s_waitcnt lgkmcnt(0)
	v_cndmask_b32_e64 v90, v91, 0, s[6:7]
	v_add_f32_e32 v29, v90, v29
	s_nop 1
	v_add_f32_dpp v90, v29, v29 quad_perm:[1,0,3,2] row_mask:0xf bank_mask:0xf
	v_add_u32_e32 v105, v222, v92
	s_nop 1
	v_add_f32_dpp v29, v90, v90 quad_perm:[2,3,0,1] row_mask:0xf bank_mask:0xf
	s_and_saveexec_b64 s[68:69], s[10:11]
	s_cbranch_execz .LBB0_605
	ds_write_b32 v105, v29
.LBB0_605:
	s_or_b64 exec, exec, s[68:69]
	v_mov_b32_e32 v29, v28
	v_pk_mul_f32 v[36:37], v[28:29], v[36:37]
	v_pk_mul_f32 v[38:39], v[28:29], v[38:39]
	v_add_f32_e32 v92, v36, v37
	s_waitcnt lgkmcnt(0)
	v_add_f32_e32 v90, v38, v39
	v_add_f32_e32 v92, v92, v90
	ds_bpermute_b32 v90, v219, v39
	s_waitcnt lgkmcnt(0)
	v_cndmask_b32_e64 v91, v90, v91, s[6:7]
	v_add_f32_e32 v91, v92, v91
	s_nop 1
	v_add_f32_dpp v92, v91, v91 quad_perm:[1,0,3,2] row_mask:0xf bank_mask:0xf
	s_nop 1
	v_add_f32_dpp v91, v92, v92 quad_perm:[2,3,0,1] row_mask:0xf bank_mask:0xf
	s_and_saveexec_b64 s[68:69], s[10:11]
	s_cbranch_execz .LBB0_607
	ds_write_b32 v105, v91 offset:16
.LBB0_607:
	s_or_b64 exec, exec, s[68:69]
	v_pk_mul_f32 v[40:41], v[28:29], v[40:41]
	v_pk_mul_f32 v[42:43], v[28:29], v[42:43]
	s_waitcnt lgkmcnt(0)
	v_add_f32_e32 v92, v40, v41
	v_add_f32_e32 v91, v42, v43
	v_add_f32_e32 v92, v92, v91
	ds_bpermute_b32 v91, v219, v43
	s_waitcnt lgkmcnt(0)
	v_cndmask_b32_e64 v90, v91, v90, s[6:7]
	v_add_f32_e32 v90, v92, v90
	s_nop 1
	v_add_f32_dpp v92, v90, v90 quad_perm:[1,0,3,2] row_mask:0xf bank_mask:0xf
	s_nop 1
	v_add_f32_dpp v90, v92, v92 quad_perm:[2,3,0,1] row_mask:0xf bank_mask:0xf
	s_and_saveexec_b64 s[68:69], s[10:11]
	s_cbranch_execz .LBB0_609
	ds_write_b32 v105, v90 offset:32
.LBB0_609:
	s_or_b64 exec, exec, s[68:69]
	v_pk_mul_f32 v[46:47], v[28:29], v[46:47]
	v_pk_mul_f32 v[48:49], v[28:29], v[48:49]
	s_waitcnt lgkmcnt(0)
	v_add_f32_e32 v92, v46, v47
	v_add_f32_e32 v90, v48, v49
	v_add_f32_e32 v92, v92, v90
	ds_bpermute_b32 v90, v219, v49
	s_waitcnt lgkmcnt(0)
	v_cndmask_b32_e64 v91, v90, v91, s[6:7]
	v_add_f32_e32 v91, v92, v91
	s_nop 1
	v_add_f32_dpp v92, v91, v91 quad_perm:[1,0,3,2] row_mask:0xf bank_mask:0xf
	s_nop 1
	v_add_f32_dpp v91, v92, v92 quad_perm:[2,3,0,1] row_mask:0xf bank_mask:0xf
	s_and_saveexec_b64 s[68:69], s[10:11]
	s_cbranch_execz .LBB0_611
	ds_write_b32 v105, v91 offset:48
.LBB0_611:
	s_or_b64 exec, exec, s[68:69]
	v_pk_mul_f32 v[84:85], v[28:29], v[84:85]
	v_pk_mul_f32 v[86:87], v[28:29], v[86:87]
	s_waitcnt lgkmcnt(0)
	v_add_f32_e32 v92, v84, v85
	v_add_f32_e32 v91, v86, v87
	v_add_f32_e32 v92, v92, v91
	ds_bpermute_b32 v91, v219, v87
	s_waitcnt lgkmcnt(0)
	v_cndmask_b32_e64 v90, v91, v90, s[6:7]
	v_add_f32_e32 v90, v92, v90
	s_nop 1
	v_add_f32_dpp v92, v90, v90 quad_perm:[1,0,3,2] row_mask:0xf bank_mask:0xf
	s_nop 1
	v_add_f32_dpp v90, v92, v92 quad_perm:[2,3,0,1] row_mask:0xf bank_mask:0xf
	s_and_saveexec_b64 s[68:69], s[10:11]
	s_cbranch_execz .LBB0_613
	ds_write_b32 v105, v90 offset:64
.LBB0_613:
	s_or_b64 exec, exec, s[68:69]
	v_pk_mul_f32 v[96:97], v[28:29], v[82:83]
	v_pk_mul_f32 v[98:99], v[28:29], v[88:89]
	v_add_f32_e32 v83, v96, v97
	v_add_f32_e32 v82, v98, v99
	v_add_f32_e32 v83, v83, v82
	ds_bpermute_b32 v82, v219, v99
	s_waitcnt lgkmcnt(0)
	v_cndmask_b32_e64 v88, v82, v91, s[6:7]
	v_add_f32_e32 v83, v83, v88
	s_nop 1
	v_add_f32_dpp v88, v83, v83 quad_perm:[1,0,3,2] row_mask:0xf bank_mask:0xf
	s_nop 1
	v_add_f32_dpp v83, v88, v88 quad_perm:[2,3,0,1] row_mask:0xf bank_mask:0xf
	s_and_saveexec_b64 s[68:69], s[10:11]
	s_cbranch_execz .LBB0_615
	ds_write_b32 v105, v83 offset:80
; __device__ __forceinline__ void attn_phase(const bf16_t* __restrict__ proj, const bf16_t* __restrict__ KC,
;                            const bf16_t* __restrict__ VCT, const bf16_t* __restrict__ VT,
;                            bf16_t* __restrict__ mixed) {
;     ...
;       float rot_prev = 0.f;
; #pragma unroll
;       for (int mt = 0; mt < 16; ++mt) {
;         sc[mt][0] *= inv; sc[mt][1] *= inv; sc[mt][2] *= inv; sc[mt][3] *= inv;
;         float own = (sc[mt][0] + sc[mt][1]) + (sc[mt][2] + sc[mt][3]);
;         float rot = __shfl(sc[mt][3], (lane + 48) & 63);
;         float prev = (quad == 0) ? rot_prev : rot;
;         rot_prev = rot;
;         float ps = own + prev;
;         ps += __shfl_xor(ps, 1);
;         ps += __shfl_xor(ps, 2);
;         if (r == 0) pslc[(w * 8 + qs * 4 + tl) * 64 + mt * 4 + quad] = ps;
;       }
.LBB0_615:
	s_or_b64 exec, exec, s[68:69]
	v_pk_mul_f32 v[100:101], v[28:29], v[78:79]
	v_pk_mul_f32 v[190:191], v[28:29], v[80:81]
	v_add_f32_e32 v79, v100, v101
	v_add_f32_e32 v78, v190, v191
	v_add_f32_e32 v79, v79, v78
	ds_bpermute_b32 v78, v219, v191
	s_waitcnt lgkmcnt(0)
	v_cndmask_b32_e64 v80, v78, v82, s[6:7]
	v_add_f32_e32 v79, v79, v80
	s_nop 1
	v_add_f32_dpp v80, v79, v79 quad_perm:[1,0,3,2] row_mask:0xf bank_mask:0xf
	s_nop 1
	v_add_f32_dpp v79, v80, v80 quad_perm:[2,3,0,1] row_mask:0xf bank_mask:0xf
	s_and_saveexec_b64 s[68:69], s[10:11]
	s_cbranch_execz .LBB0_617
	ds_write_b32 v105, v79 offset:96
.LBB0_617:
	s_or_b64 exec, exec, s[68:69]
	v_pk_mul_f32 v[204:205], v[28:29], v[72:73]
	v_pk_mul_f32 v[206:207], v[28:29], v[76:77]
	v_add_f32_e32 v73, v204, v205
	v_add_f32_e32 v72, v206, v207
	v_add_f32_e32 v73, v73, v72
	ds_bpermute_b32 v72, v219, v207
	s_waitcnt lgkmcnt(0)
	v_cndmask_b32_e64 v76, v72, v78, s[6:7]
	v_add_f32_e32 v73, v73, v76
	s_nop 1
	v_add_f32_dpp v76, v73, v73 quad_perm:[1,0,3,2] row_mask:0xf bank_mask:0xf
	s_nop 1
	v_add_f32_dpp v73, v76, v76 quad_perm:[2,3,0,1] row_mask:0xf bank_mask:0xf
	s_and_saveexec_b64 s[68:69], s[10:11]
	s_cbranch_execz .LBB0_619
	ds_write_b32 v105, v73 offset:112
.LBB0_619:
	s_or_b64 exec, exec, s[68:69]
	v_pk_mul_f32 v[64:65], v[28:29], v[64:65]
	v_pk_mul_f32 v[66:67], v[28:29], v[66:67]
	s_waitcnt lgkmcnt(0)
	v_add_f32_e32 v76, v64, v65
	v_add_f32_e32 v73, v66, v67
	v_add_f32_e32 v73, v76, v73
	ds_bpermute_b32 v76, v219, v67
	s_waitcnt lgkmcnt(0)
	v_cndmask_b32_e64 v72, v76, v72, s[6:7]
	v_add_f32_e32 v72, v73, v72
	s_nop 1
	v_add_f32_dpp v73, v72, v72 quad_perm:[1,0,3,2] row_mask:0xf bank_mask:0xf
	s_nop 1
	v_add_f32_dpp v72, v73, v73 quad_perm:[2,3,0,1] row_mask:0xf bank_mask:0xf
	s_and_saveexec_b64 s[68:69], s[10:11]
	s_cbranch_execz .LBB0_621
	ds_write_b32 v105, v72 offset:128
.LBB0_621:
	s_or_b64 exec, exec, s[68:69]
	s_waitcnt lgkmcnt(0)
	v_pk_mul_f32 v[72:73], v[28:29], v[70:71]
	ds_bpermute_b32 v77, v219, v73
	v_pk_mul_f32 v[68:69], v[28:29], v[68:69]
	v_add_f32_e32 v70, v72, v73
	v_add_f32_e32 v71, v68, v69
	v_add_f32_e32 v70, v71, v70
	s_waitcnt lgkmcnt(0)
	v_cndmask_b32_e64 v71, v77, v76, s[6:7]
	v_add_f32_e32 v70, v70, v71
	s_nop 1
	v_add_f32_dpp v71, v70, v70 quad_perm:[1,0,3,2] row_mask:0xf bank_mask:0xf
	s_nop 1
	v_add_f32_dpp v70, v71, v71 quad_perm:[2,3,0,1] row_mask:0xf bank_mask:0xf
	s_and_saveexec_b64 s[68:69], s[10:11]
	s_cbranch_execz .LBB0_623
	ds_write_b32 v105, v70 offset:144
.LBB0_623:
	s_or_b64 exec, exec, s[68:69]
	s_waitcnt lgkmcnt(0)
	v_pk_mul_f32 v[70:71], v[28:29], v[62:63]
	v_pk_mul_f32 v[74:75], v[28:29], v[74:75]
	v_add_f32_e32 v63, v70, v71
	v_add_f32_e32 v62, v74, v75
	v_add_f32_e32 v63, v63, v62
	ds_bpermute_b32 v62, v219, v75
	s_waitcnt lgkmcnt(0)
	v_cndmask_b32_e64 v76, v62, v77, s[6:7]
	v_add_f32_e32 v63, v63, v76
	s_nop 1
	v_add_f32_dpp v76, v63, v63 quad_perm:[1,0,3,2] row_mask:0xf bank_mask:0xf
	s_nop 1
	v_add_f32_dpp v63, v76, v76 quad_perm:[2,3,0,1] row_mask:0xf bank_mask:0xf
	s_and_saveexec_b64 s[68:69], s[10:11]
	s_cbranch_execz .LBB0_625
	ds_write_b32 v105, v63 offset:160
.LBB0_625:
	s_or_b64 exec, exec, s[68:69]
	v_pk_mul_f32 v[80:81], v[28:29], v[58:59]
	v_pk_mul_f32 v[82:83], v[28:29], v[60:61]
	v_add_f32_e32 v59, v80, v81
	v_add_f32_e32 v58, v82, v83
	v_add_f32_e32 v59, v59, v58
	ds_bpermute_b32 v58, v219, v83
	s_waitcnt lgkmcnt(0)
	v_cndmask_b32_e64 v60, v58, v62, s[6:7]
	v_add_f32_e32 v59, v59, v60
	s_nop 1
	v_add_f32_dpp v60, v59, v59 quad_perm:[1,0,3,2] row_mask:0xf bank_mask:0xf
	s_nop 1
	v_add_f32_dpp v59, v60, v60 quad_perm:[2,3,0,1] row_mask:0xf bank_mask:0xf
	s_and_saveexec_b64 s[68:69], s[10:11]
	s_cbranch_execz .LBB0_627
	ds_write_b32 v105, v59 offset:176
.LBB0_627:
	s_or_b64 exec, exec, s[68:69]
	v_pk_mul_f32 v[76:77], v[28:29], v[54:55]
	v_pk_mul_f32 v[78:79], v[28:29], v[56:57]
	v_add_f32_e32 v55, v76, v77
	v_add_f32_e32 v54, v78, v79
	v_add_f32_e32 v55, v55, v54
	ds_bpermute_b32 v54, v219, v79
	s_waitcnt lgkmcnt(0)
	v_cndmask_b32_e64 v56, v54, v58, s[6:7]
	v_add_f32_e32 v55, v55, v56
	s_nop 1
	v_add_f32_dpp v56, v55, v55 quad_perm:[1,0,3,2] row_mask:0xf bank_mask:0xf
	s_nop 1
	v_add_f32_dpp v55, v56, v56 quad_perm:[2,3,0,1] row_mask:0xf bank_mask:0xf
	s_and_saveexec_b64 s[68:69], s[10:11]
	s_cbranch_execz .LBB0_629
	ds_write_b32 v105, v55 offset:192
.LBB0_629:
	s_or_b64 exec, exec, s[68:69]
	v_pk_mul_f32 v[88:89], v[28:29], v[50:51]
	v_pk_mul_f32 v[92:93], v[28:29], v[52:53]
	v_add_f32_e32 v51, v88, v89
	v_add_f32_e32 v50, v92, v93
	v_add_f32_e32 v51, v51, v50
	ds_bpermute_b32 v50, v219, v93
	s_waitcnt lgkmcnt(0)
	v_cndmask_b32_e64 v52, v50, v54, s[6:7]
	v_add_f32_e32 v51, v51, v52
	s_nop 1
	v_add_f32_dpp v52, v51, v51 quad_perm:[1,0,3,2] row_mask:0xf bank_mask:0xf
	s_nop 1
	v_add_f32_dpp v51, v52, v52 quad_perm:[2,3,0,1] row_mask:0xf bank_mask:0xf
	s_and_saveexec_b64 s[68:69], s[10:11]
	s_cbranch_execz .LBB0_631
	ds_write_b32 v105, v51 offset:208
.LBB0_631:
	s_or_b64 exec, exec, s[68:69]
	v_pk_mul_f32 v[90:91], v[28:29], v[30:31]
	v_pk_mul_f32 v[94:95], v[28:29], v[44:45]
	v_add_f32_e32 v31, v90, v91
	v_add_f32_e32 v30, v94, v95
	v_add_f32_e32 v31, v31, v30
	ds_bpermute_b32 v30, v219, v95
	s_waitcnt lgkmcnt(0)
	v_cndmask_b32_e64 v44, v30, v50, s[6:7]
	v_add_f32_e32 v31, v31, v44
	s_nop 1
	v_add_f32_dpp v44, v31, v31 quad_perm:[1,0,3,2] row_mask:0xf bank_mask:0xf
	s_nop 1
	v_add_f32_dpp v31, v44, v44 quad_perm:[2,3,0,1] row_mask:0xf bank_mask:0xf
	s_and_saveexec_b64 s[68:69], s[10:11]
	s_cbranch_execz .LBB0_633
	ds_write_b32 v105, v31 offset:224
.LBB0_633:
	s_or_b64 exec, exec, s[68:69]
	v_pk_mul_f32 v[102:103], v[28:29], v[24:25]
	v_pk_mul_f32 v[202:203], v[28:29], v[26:27]
	v_add_f32_e32 v25, v102, v103
	v_add_f32_e32 v24, v202, v203
	v_add_f32_e32 v24, v25, v24
	ds_bpermute_b32 v25, v219, v203
	s_waitcnt lgkmcnt(0)
	v_cndmask_b32_e64 v25, v25, v30, s[6:7]
	v_add_f32_e32 v24, v24, v25
	s_nop 1
	v_add_f32_dpp v25, v24, v24 quad_perm:[1,0,3,2] row_mask:0xf bank_mask:0xf
	s_nop 1
	v_add_f32_dpp v24, v25, v25 quad_perm:[2,3,0,1] row_mask:0xf bank_mask:0xf
	s_and_saveexec_b64 s[68:69], s[10:11]
	s_cbranch_execz .LBB0_635
	ds_write_b32 v105, v24 offset:240

; __device__ __forceinline__ void attn_phase(const bf16_t* __restrict__ proj, const bf16_t* __restrict__ KC,
;                            const bf16_t* __restrict__ VCT, const bf16_t* __restrict__ VT,
;                            bf16_t* __restrict__ mixed) {
;     ...
;     unsigned long long mymask[2] = {0ull, 0ull}, wunion = 0ull;
;     {
;       const int cur = ttile;
;       if (cur < 16) {
;         const unsigned long long m = (2ull << cur) - 1ull;
;         mymask[0] = m;
;         mymask[1] = m;
;         wunion = m;
;       } else {
;         unsigned long long mm0 = 0ull, mm1 = 0ull;
; #pragma nounroll
;         for (int t8 = 0; t8 < 8; ++t8) {
;           const int J = lane;
;           const float psv = pslc[(w * 8 + t8) * 64 + J];
;           const bool valid = J <= cur;
;           const bool forced = (J == 0) || (valid && (J > cur - 2));
;           const float score = forced ? 1e9f : (valid ? psv : -1.0f);
;           const int sbits = __float_as_int(score);
;           int cnt = 0;
; #pragma unroll 8
;           for (int i = 0; i < 64; ++i) {
;             const float si = __int_as_float(__builtin_amdgcn_readlane(sbits, i));
;             cnt += ((si > score) || (si == score && i < J)) ? 1 : 0;
;           }
;           const unsigned long long m = __ballot(cnt < 16);
;           const bool mine = (tl == (t8 & 3));
;           if (mine && (t8 < 4)) mm0 = m;
;           if (mine && (t8 >= 4)) mm1 = m;
;           wunion |= m;
;         }
;         mymask[0] = mm0;
;         mymask[1] = mm1;
;       }
.LBB0_647:
	s_cmp_lt_u32 s96, 16
	s_waitcnt lgkmcnt(0)
	s_barrier
	s_cbranch_scc1 .LBB0_653
	s_add_i32 s10, s96, -2
	v_cmp_ge_u32_e32 vcc, s96, v183
	v_cmp_lt_i32_e64 s[10:11], s10, v183
	v_cmp_eq_u32_e64 s[6:7], 0, v183
	s_and_b64 s[10:11], vcc, s[10:11]
	v_lshl_add_u32 v0, v183, 2, s79
	s_or_b64 s[6:7], s[6:7], s[10:11]
	v_lshl_add_u32 v24, s72, 8, v0
	ds_read_b32 v16, v24 offset:0
	ds_read_b32 v17, v24 offset:256
	ds_read_b32 v18, v24 offset:512
	ds_read_b32 v19, v24 offset:768
	ds_read_b32 v20, v24 offset:1024
	ds_read_b32 v21, v24 offset:1280
	ds_read_b32 v22, v24 offset:1536
	ds_read_b32 v23, v24 offset:1792
	v_mov_b64_e32 v[160:161], 0
	s_mov_b64 s[16:17], 0
	v_mov_b64_e32 v[162:163], 0
	s_add_i32 s101, s96, 2
	s_and_b32 s101, s101, -2
	s_waitcnt lgkmcnt(0)
	v_cndmask_b32_e32 v16, -1.0, v16, vcc
	v_cndmask_b32_e32 v17, -1.0, v17, vcc
	v_cndmask_b32_e32 v18, -1.0, v18, vcc
	v_cndmask_b32_e32 v19, -1.0, v19, vcc
	v_cndmask_b32_e32 v20, -1.0, v20, vcc
	v_cndmask_b32_e32 v21, -1.0, v21, vcc
	v_cndmask_b32_e32 v22, -1.0, v22, vcc
	v_cndmask_b32_e32 v23, -1.0, v23, vcc
	v_cndmask_b32_e64 v16, v16, v215, s[6:7]
	v_cndmask_b32_e64 v17, v17, v215, s[6:7]
	v_cndmask_b32_e64 v18, v18, v215, s[6:7]
	v_cndmask_b32_e64 v19, v19, v215, s[6:7]
	v_cndmask_b32_e64 v20, v20, v215, s[6:7]
	v_cndmask_b32_e64 v21, v21, v215, s[6:7]
	v_cndmask_b32_e64 v22, v22, v215, s[6:7]
	v_cndmask_b32_e64 v23, v23, v215, s[6:7]
	v_xor_b32_e32 v1, 0x80000000, v16
	v_sub_u32_e32 v0, 63, v183
	v_xor_b32_e32 v3, 0x80000000, v17
	v_sub_u32_e32 v2, 63, v183
	v_xor_b32_e32 v5, 0x80000000, v18
	v_sub_u32_e32 v4, 63, v183
	v_xor_b32_e32 v7, 0x80000000, v19
	v_sub_u32_e32 v6, 63, v183
	v_xor_b32_e32 v9, 0x80000000, v20
	v_sub_u32_e32 v8, 63, v183
	v_xor_b32_e32 v11, 0x80000000, v21
	v_sub_u32_e32 v10, 63, v183
	v_xor_b32_e32 v13, 0x80000000, v22
	v_sub_u32_e32 v12, 63, v183
	v_xor_b32_e32 v15, 0x80000000, v23
	v_sub_u32_e32 v14, 63, v183
	v_mov_b32_e32 v24, 0
	v_mov_b32_e32 v25, 0
	v_mov_b32_e32 v26, 0
	v_mov_b32_e32 v27, 0
	v_mov_b32_e32 v28, 0
	v_mov_b32_e32 v29, 0
	v_mov_b32_e32 v30, 0
	v_mov_b32_e32 v31, 0
	s_mov_b32 s100, 0
.Ltk1_p0:
	s_sub_i32 s8, 63, s100
	s_sub_i32 s10, 63, s100
	s_sub_i32 s12, 63, s100
	s_sub_i32 s14, 63, s100
	v_readlane_b32 s9, v1, s100
	v_readlane_b32 s11, v3, s100
	v_readlane_b32 s13, v5, s100
	v_readlane_b32 s15, v7, s100
	v_cmp_gt_u64_e32 vcc, s[8:9], v[0:1]
	v_cmp_gt_u64_e64 s[6:7], s[10:11], v[2:3]
	v_cmp_gt_u64_e64 s[98:99], s[12:13], v[4:5]
	v_addc_co_u32_e64 v24, vcc, 0, v24, vcc
	v_cmp_gt_u64_e32 vcc, s[14:15], v[6:7]
	v_addc_co_u32_e64 v25, s[6:7], 0, v25, s[6:7]
	v_addc_co_u32_e64 v26, s[98:99], 0, v26, s[98:99]
	v_addc_co_u32_e64 v27, vcc, 0, v27, vcc
	s_add_i32 s100, s100, 1
	s_sub_i32 s8, 63, s100
	s_sub_i32 s10, 63, s100
	s_sub_i32 s12, 63, s100
	s_sub_i32 s14, 63, s100
	v_readlane_b32 s9, v1, s100
	v_readlane_b32 s11, v3, s100
	v_readlane_b32 s13, v5, s100
	v_readlane_b32 s15, v7, s100
	v_cmp_gt_u64_e32 vcc, s[8:9], v[0:1]
	v_cmp_gt_u64_e64 s[6:7], s[10:11], v[2:3]
	v_cmp_gt_u64_e64 s[98:99], s[12:13], v[4:5]
	v_addc_co_u32_e64 v24, vcc, 0, v24, vcc
	v_cmp_gt_u64_e32 vcc, s[14:15], v[6:7]
	v_addc_co_u32_e64 v25, s[6:7], 0, v25, s[6:7]
	v_addc_co_u32_e64 v26, s[98:99], 0, v26, s[98:99]
	v_addc_co_u32_e64 v27, vcc, 0, v27, vcc
	s_add_i32 s100, s100, 1
	s_cmp_lt_u32 s100, s101
	s_cbranch_scc1 .Ltk1_p0
	s_mov_b32 s100, 0
.Ltk1_p1:
	s_sub_i32 s8, 63, s100
	s_sub_i32 s10, 63, s100
	s_sub_i32 s12, 63, s100
	s_sub_i32 s14, 63, s100
	v_readlane_b32 s9, v9, s100
	v_readlane_b32 s11, v11, s100
	v_readlane_b32 s13, v13, s100
	v_readlane_b32 s15, v15, s100
	v_cmp_gt_u64_e32 vcc, s[8:9], v[8:9]
	v_cmp_gt_u64_e64 s[6:7], s[10:11], v[10:11]
	v_cmp_gt_u64_e64 s[98:99], s[12:13], v[12:13]
	v_addc_co_u32_e64 v28, vcc, 0, v28, vcc
	v_cmp_gt_u64_e32 vcc, s[14:15], v[14:15]
	v_addc_co_u32_e64 v29, s[6:7], 0, v29, s[6:7]
	v_addc_co_u32_e64 v30, s[98:99], 0, v30, s[98:99]
	v_addc_co_u32_e64 v31, vcc, 0, v31, vcc
	s_add_i32 s100, s100, 1
	s_sub_i32 s8, 63, s100
	s_sub_i32 s10, 63, s100
	s_sub_i32 s12, 63, s100
	s_sub_i32 s14, 63, s100
	v_readlane_b32 s9, v9, s100
	v_readlane_b32 s11, v11, s100
	v_readlane_b32 s13, v13, s100
	v_readlane_b32 s15, v15, s100
	v_cmp_gt_u64_e32 vcc, s[8:9], v[8:9]
	v_cmp_gt_u64_e64 s[6:7], s[10:11], v[10:11]
	v_cmp_gt_u64_e64 s[98:99], s[12:13], v[12:13]
	v_addc_co_u32_e64 v28, vcc, 0, v28, vcc
	v_cmp_gt_u64_e32 vcc, s[14:15], v[14:15]
	v_addc_co_u32_e64 v29, s[6:7], 0, v29, s[6:7]
	v_addc_co_u32_e64 v30, s[98:99], 0, v30, s[98:99]
	v_addc_co_u32_e64 v31, vcc, 0, v31, vcc
	s_add_i32 s100, s100, 1
	s_cmp_lt_u32 s100, s101
	s_cbranch_scc1 .Ltk1_p1
	v_cmp_gt_u32_e64 s[10:11], 16, v24
	v_cmp_eq_u32_e64 s[12:13], 0, v193
	s_nop 1
	v_mov_b32_e32 v16, s10
	v_mov_b32_e32 v17, s11
	s_or_b64 s[16:17], s[16:17], s[10:11]
	v_cndmask_b32_e64 v162, v162, v16, s[12:13]
	v_cndmask_b32_e64 v163, v163, v17, s[12:13]
	v_cmp_gt_u32_e64 s[10:11], 16, v25
	v_cmp_eq_u32_e64 s[12:13], 1, v193
	s_nop 1
	v_mov_b32_e32 v16, s10
	v_mov_b32_e32 v17, s11
	s_or_b64 s[16:17], s[16:17], s[10:11]
	v_cndmask_b32_e64 v162, v162, v16, s[12:13]
	v_cndmask_b32_e64 v163, v163, v17, s[12:13]
	v_cmp_gt_u32_e64 s[10:11], 16, v26
	v_cmp_eq_u32_e64 s[12:13], 2, v193
	s_nop 1
	v_mov_b32_e32 v16, s10
	v_mov_b32_e32 v17, s11
	s_or_b64 s[16:17], s[16:17], s[10:11]
	v_cndmask_b32_e64 v162, v162, v16, s[12:13]
	v_cndmask_b32_e64 v163, v163, v17, s[12:13]
	v_cmp_gt_u32_e64 s[10:11], 16, v27
	v_cmp_eq_u32_e64 s[12:13], 3, v193
	s_nop 1
	v_mov_b32_e32 v16, s10
	v_mov_b32_e32 v17, s11
	s_or_b64 s[16:17], s[16:17], s[10:11]
	v_cndmask_b32_e64 v162, v162, v16, s[12:13]
	v_cndmask_b32_e64 v163, v163, v17, s[12:13]
	v_cmp_gt_u32_e64 s[10:11], 16, v28
	v_cmp_eq_u32_e64 s[12:13], 0, v193
	s_nop 1
	v_mov_b32_e32 v16, s10
	v_mov_b32_e32 v17, s11
	s_or_b64 s[16:17], s[16:17], s[10:11]
	v_cndmask_b32_e64 v160, v160, v16, s[12:13]
	v_cndmask_b32_e64 v161, v161, v17, s[12:13]
	v_cmp_gt_u32_e64 s[10:11], 16, v29
	v_cmp_eq_u32_e64 s[12:13], 1, v193
	s_nop 1
	v_mov_b32_e32 v16, s10
	v_mov_b32_e32 v17, s11
	s_or_b64 s[16:17], s[16:17], s[10:11]
	v_cndmask_b32_e64 v160, v160, v16, s[12:13]
	v_cndmask_b32_e64 v161, v161, v17, s[12:13]
	v_cmp_gt_u32_e64 s[10:11], 16, v30
	v_cmp_eq_u32_e64 s[12:13], 2, v193
	s_nop 1
	v_mov_b32_e32 v16, s10
	v_mov_b32_e32 v17, s11
	s_or_b64 s[16:17], s[16:17], s[10:11]
	v_cndmask_b32_e64 v160, v160, v16, s[12:13]
	v_cndmask_b32_e64 v161, v161, v17, s[12:13]
	v_cmp_gt_u32_e64 s[10:11], 16, v31
	v_cmp_eq_u32_e64 s[12:13], 3, v193
	s_nop 1
	v_mov_b32_e32 v16, s10
	v_mov_b32_e32 v17, s11
	s_or_b64 s[16:17], s[16:17], s[10:11]
	v_cndmask_b32_e64 v160, v160, v16, s[12:13]
	v_cndmask_b32_e64 v161, v161, v17, s[12:13]
	s_branch .LBB0_655

; __global__ void __launch_bounds__(NTHREADS) fwd_megakernel(Params p_unused) {
	.amdhsa_kernel _Z14fwd_megakernel6Params
		.amdhsa_group_segment_fixed_size 16
		.amdhsa_private_segment_fixed_size 0
		.amdhsa_kernarg_size 368
		.amdhsa_user_sgpr_count 2
		.amdhsa_user_sgpr_dispatch_ptr 0
		.amdhsa_user_sgpr_queue_ptr 0
		.amdhsa_user_sgpr_kernarg_segment_ptr 1
		.amdhsa_user_sgpr_dispatch_id 0
		.amdhsa_user_sgpr_kernarg_preload_length 0
		.amdhsa_user_sgpr_kernarg_preload_offset 0
		.amdhsa_user_sgpr_private_segment_size 0
		.amdhsa_uses_dynamic_stack 0
		.amdhsa_enable_private_segment 0
		.amdhsa_system_sgpr_workgroup_id_x 1
		.amdhsa_system_sgpr_workgroup_id_y 0
		.amdhsa_system_sgpr_workgroup_id_z 0
		.amdhsa_system_sgpr_workgroup_info 0
		.amdhsa_system_vgpr_workitem_id 2
		.amdhsa_next_free_vgpr 256
		.amdhsa_next_free_sgpr 102
		.amdhsa_accum_offset 256
		.amdhsa_reserve_vcc 1
		.amdhsa_float_round_mode_32 0
		.amdhsa_float_round_mode_16_64 0
		.amdhsa_float_denorm_mode_32 3
		.amdhsa_float_denorm_mode_16_64 3
		.amdhsa_dx10_clamp 1
		.amdhsa_ieee_mode 1
		.amdhsa_fp16_overflow 0
		.amdhsa_tg_split 0
		.amdhsa_exception_fp_ieee_invalid_op 0
		.amdhsa_exception_fp_denorm_src 0
		.amdhsa_exception_fp_ieee_div_zero 0
		.amdhsa_exception_fp_ieee_overflow 0
		.amdhsa_exception_fp_ieee_underflow 0
		.amdhsa_exception_fp_ieee_inexact 0
		.amdhsa_exception_int_div_zero 0
	.end_amdhsa_kernel

amdhsa.kernels:
  - .agpr_count:     0
    .args:
      - .offset:         0
        .size:           112
        .value_kind:     by_value
      - .offset:         112
        .size:           4
        .value_kind:     hidden_block_count_x
      - .offset:         116
        .size:           4
        .value_kind:     hidden_block_count_y
      - .offset:         120
        .size:           4
        .value_kind:     hidden_block_count_z
      - .offset:         124
        .size:           2
        .value_kind:     hidden_group_size_x
      - .offset:         126
        .size:           2
        .value_kind:     hidden_group_size_y
      - .offset:         128
        .size:           2
        .value_kind:     hidden_group_size_z
      - .offset:         130
        .size:           2
        .value_kind:     hidden_remainder_x
      - .offset:         132
        .size:           2
        .value_kind:     hidden_remainder_y
      - .offset:         134
        .size:           2
        .value_kind:     hidden_remainder_z
      - .offset:         152
        .size:           8
        .value_kind:     hidden_global_offset_x
      - .offset:         160
        .size:           8
        .value_kind:     hidden_global_offset_y
      - .offset:         168
        .size:           8
        .value_kind:     hidden_global_offset_z
      - .offset:         176
        .size:           2
        .value_kind:     hidden_grid_dims
      - .offset:         200
        .size:           8
        .value_kind:     hidden_multigrid_sync_arg
      - .offset:         232
        .size:           4
        .value_kind:     hidden_dynamic_lds_size
    .group_segment_fixed_size: 16
    .kernarg_segment_align: 8
    .kernarg_segment_size: 368
    .language:       OpenCL C
    .language_version:
      - 2
      - 0
    .max_flat_workgroup_size: 512
    .name:           _Z14fwd_megakernel6Params
    .private_segment_fixed_size: 0
    .sgpr_count:     108
    .sgpr_spill_count: 8
    .symbol:         _Z14fwd_megakernel6Params.kd
    .uniform_work_group_size: 1
    .uses_dynamic_stack: false
    .vgpr_count:     256
    .vgpr_spill_count: 0
    .wavefront_size: 64
